# seam-hosted weight conversion: the W2GU items [17792,21888) of the P0 prologue are now converted by two idle waves per workgroup during grid-barrier waits (seams 0-3,6-9), P0 prologue shortened accord
# speedup vs baseline: 1.0056x; 1.0056x over previous
; #define LAS __attribute__((address_space(3)))
; __device__ __forceinline__ TrItem tr_decode(int it, const float* const* in, unsigned char* ws, int lane) {
;     int r = it, kind = 0, ndb = 32, N = D, K = D; const float *W, *W2 = nullptr, *gain = nullptr; bf16_t* WT; bool nts = false, woh = false;
;     if (r < 5632) { kind = 1; W = in[3]; W2 = in[4]; N = FF; ndb = 176; gain = in[2]; WT = (bf16_t*)(ws + WS_W1GU); }
;     else if ((r -= 5632) < 2816) { W = in[5]; K = FF; WT = (bf16_t*)(ws + WS_W1D); }
;     else if ((r -= 2816) < 2688) { kind = 2; W = in[7]; N = INC; ndb = 84; gain = in[6]; WT = (bf16_t*)(ws + WS_WIN); nts = true; }
;     else if ((r -= 2688) < 1024) { W = in[10]; WT = (bf16_t*)(ws + WS_WOUT); nts = true; }
;     else if ((r -= 1024) < 1024) { W = in[13]; gain = in[11]; WT = (bf16_t*)(ws + WS_WQ); nts = true; }
;     else if ((r -= 1024) < 2048) { W = in[14]; N = 2 * D; ndb = 64; gain = in[12]; WT = (bf16_t*)(ws + WS_WKV); }
;     else if ((r -= 2048) < 1024) { W = in[15]; WT = (bf16_t*)(ws + WS_WO); nts = true; woh = true; }
;     else if ((r -= 1024) < 5632) { kind = 1; W = in[17]; W2 = in[18]; N = FF; ndb = 176; gain = in[16]; WT = (bf16_t*)(ws + WS_W2GU); nts = true; }
;     else { r -= 5632; W = in[19]; K = FF; WT = (bf16_t*)(ws + WS_W2D); }
;     __device__ __forceinline__ int count() const { return (e0 - b0) + (e1 - b1) + (e2 - b2); }
; __device__ __forceinline__ void tr_all(const float* const* in, unsigned char* ws, LAS float* scr, int gw, int ngw, int lane, const TrRanges rg) {
;     const int TR_CNT = rg.count();
;     if (gw >= TR_CNT) return;
;     TrItem cur = tr_decode(rg.item(gw), in, ws, lane);
.LBB0_158:
	s_andn2_b64 vcc, exec, s[0:1]
	s_cbranch_vccnz .LBB0_280
	s_cmpk_gt_i32 s4, 0xbff
	s_cbranch_scc1 .LBB0_271
	s_cmpk_lt_i32 s4, 0x1000
	s_movk_i32 s0, 0x3380
	s_cselect_b32 s0, s0, 0x3380
	s_add_i32 s5, s4, s0
	s_cmpk_lt_i32 s5, 0x1600
	s_mov_b64 s[22:23], -1
	s_cbranch_scc1 .LBB0_168
	s_cmpk_gt_u32 s5, 0x20ff
	s_cbranch_scc0 .LBB0_169
	s_cmpk_gt_u32 s5, 0x2b7f
	s_cbranch_scc0 .LBB0_170
	s_cmpk_gt_u32 s5, 0x2f7f
	s_cbranch_scc0 .LBB0_171
	s_cmpk_gt_u32 s5, 0x337f
	s_cbranch_scc0 .LBB0_172
	s_cmpk_gt_u32 s5, 0x3b7f
	s_cbranch_scc0 .LBB0_173
	s_cmpk_gt_u32 s5, 0x3f7f
	s_mov_b64 s[26:27], -1
	s_cbranch_scc0 .LBB0_174
	v_readlane_b32 s40, v254, 4
	v_readlane_b32 s41, v254, 5
	v_readlane_b32 s42, v254, 6
	v_readlane_b32 s43, v254, 7
	v_readlane_b32 s44, v254, 8
	v_readlane_b32 s45, v254, 9
	s_add_i32 s34, s5, 0xffffc080
	s_mov_b64 s[18:19], 0
	v_readlane_b32 s46, v254, 10
	v_readlane_b32 s47, v254, 11
	s_mov_b64 s[16:17], s[42:43]
	s_mov_b64 s[0:1], s[44:45]
	s_mov_b64 s[14:15], s[40:41]
	s_branch .LBB0_175

;     __device__ __forceinline__ int count() const { return (e0 - b0) + (e1 - b1) + (e2 - b2); }
; __device__ __forceinline__ void tr_all(const float* const* in, unsigned char* ws, LAS float* scr, int gw, int ngw, int lane, const TrRanges rg) {
;     ...
;     for (int it = gw; it < TR_CNT; it += ngw) {
;         const int nit = it + ngw; const bool hn = nit < TR_CNT;
;         TrItem nx = cur; f32x4 w[16];
;         if (hn) { nx = tr_decode(rg.item(nit), in, ws, lane);
.LBB0_217:
	s_add_i32 s5, s18, s2
	s_cmpk_lt_i32 s5, 0xc00
	s_cselect_b64 s[16:17], -1, 0
	s_cmpk_gt_i32 s5, 0xbff
	s_cselect_b64 s[14:15], -1, 0
	s_and_b64 vcc, exec, s[14:15]
	v_mov_b64_e32 v[148:149], v[146:147]
	v_mov_b64_e32 v[150:151], v[142:143]
	s_mov_b32 s33, s0
	s_cbranch_vccnz .LBB0_266
	s_cmpk_lt_i32 s5, 0x1000
	s_movk_i32 s19, 0x3380
	s_cselect_b32 s19, s19, 0x3380
	s_add_i32 s26, s2, s19
	s_add_i32 s42, s19, s5
	s_add_i32 s26, s26, s18
	s_cmpk_lt_i32 s26, 0x1600
	s_mov_b64 s[28:29], -1
	s_cbranch_scc1 .LBB0_228
	s_cmpk_gt_u32 s26, 0x20ff
	s_cbranch_scc0 .LBB0_229
	s_cmpk_gt_u32 s26, 0x2b7f
	s_cbranch_scc0 .LBB0_230
	s_cmpk_gt_u32 s26, 0x2f7f
	s_cbranch_scc0 .LBB0_231
	s_cmpk_gt_u32 s26, 0x337f
	s_cbranch_scc0 .LBB0_232
	s_cmpk_gt_u32 s26, 0x3b7f
	s_cbranch_scc0 .LBB0_233
	v_readlane_b32 s48, v254, 18
	v_readlane_b32 s62, v254, 32
	v_readlane_b32 s63, v254, 33
	s_cmpk_gt_u32 s26, 0x3f7f
	s_mov_b64 s[34:35], -1
	s_mov_b64 s[18:19], s[62:63]
	s_mov_b64 s[20:21], -1
	v_readlane_b32 s49, v254, 19
	v_readlane_b32 s50, v254, 20
	v_readlane_b32 s51, v254, 21
	v_readlane_b32 s52, v254, 22
	v_readlane_b32 s53, v254, 23
	v_readlane_b32 s54, v254, 24
	v_readlane_b32 s55, v254, 25
	v_readlane_b32 s56, v254, 26
	v_readlane_b32 s57, v254, 27
	v_readlane_b32 s58, v254, 28
	v_readlane_b32 s59, v254, 29
	v_readlane_b32 s60, v254, 30
	v_readlane_b32 s61, v254, 31
	s_cbranch_scc0 .LBB0_226
	v_readlane_b32 s48, v254, 4
	v_readlane_b32 s49, v254, 5
	v_readlane_b32 s50, v254, 6
	v_readlane_b32 s51, v254, 7
	v_readlane_b32 s52, v254, 8
	v_readlane_b32 s53, v254, 9
	s_add_i32 s44, s26, 0xffffc080
	s_mov_b64 s[20:21], 0
	v_readlane_b32 s54, v254, 10
	v_readlane_b32 s55, v254, 11
	s_mov_b64 s[18:19], s[50:51]
	s_mov_b64 s[24:25], s[52:53]
	s_mov_b64 s[22:23], s[48:49]

; #define LAS __attribute__((address_space(3)))
; #define TR_LOAD(p) __builtin_nontemporal_load(p)
; __device__ __forceinline__ TrItem tr_decode(int it, const float* const* in, unsigned char* ws, int lane) {
;     ...
;     const int rh = r >> 3, rl = r & 7, nq = ndb >> DL, kbh = rh / nq, dbh = rh - kbh * nq;
;     const int kb = (kbh << KL) + (rl >> DL), db = (dbh << DL) + (rl & ((1 << DL) - 1)), d0 = db * 64, k0 = kb * 64;
;     ...
;     const int kb = r / ndb, db = r - kb * ndb, d0 = db * 64, k0 = kb * 64;
;     ...
;     const int blk = d0 + 32 * ((lane & 15) >> 3);
;     const float* src = W; int s0 = blk;
;     if (kind == 1) { const int pn = blk >> 8, bj = (blk >> 7) & 1, o = blk & 127; src = bj ? W2 : W; s0 = pn * 128 + o; }
;     else if (kind == 2) s0 = win_src(blk);
;     TrItem t; t.src = src + (size_t)(k0 + (lane >> 4)) * N + s0 + 4 * (lane & 7); t.gain = gain ? gain + k0 + 8 * (lane & 7) : nullptr;
;     t.dst = WT + (size_t)(d0 + (lane >> 3)) * K + k0 + 8 * (lane & 7); t.N = N; t.K = K; t.nts = nts && TR_NTS;
; __device__ __forceinline__ void tr_all(const float* const* in, unsigned char* ws, LAS float* scr, int gw, int ngw, int lane, const TrRanges rg) {
;     ...
;     for (int i = 0; i < 16; ++i) v[i] = TR_LOAD((const f32x4*)(cur.src + (size_t)(4 * i) * cur.N));
;     for (int it = gw; it < TR_CNT; it += ngw) {
;         const int nit = it + ngw; const bool hn = nit < TR_CNT;
;         TrItem nx = cur; f32x4 w[16];
;         if (hn) { nx = tr_decode(rg.item(nit), in, ws, lane);
; #pragma unroll
;             for (int i = 0; i < 16; ++i) w[i] = TR_LOAD((const f32x4*)(nx.src + (size_t)(4 * i) * nx.N)); }
;         LAS float* wp = scr + (lane >> 4) * 65 + 4 * (lane & 15);
; #pragma unroll
;         for (int i = 0; i < 16; ++i) { wp[(4 * i) * 65 + 0] = v[i][0]; wp[(4 * i) * 65 + 1] = v[i][1]; wp[(4 * i) * 65 + 2] = v[i][2]; wp[(4 * i) * 65 + 3] = v[i][3]; }
.Lseam_inv_0:
	v_readfirstlane_b32 s98, v1
	s_nop 0
	s_lshr_b32 s98, s98, 6
	s_cmp_lg_u32 s98, 1
	s_cbranch_scc1 .Lseam_cv_0
	s_mov_b64 exec, -1
	buffer_inv sc1
	s_waitcnt vmcnt(0)
	s_branch .LBB0_339
.Lseam_cv_0:
	s_cmp_lt_u32 s98, 2
	s_cbranch_scc1 .LBB0_339
	s_cmp_gt_u32 s98, 3
	s_cbranch_scc1 .LBB0_339
	s_mov_b64 exec, -1
	s_lshl_b32 s99, s87, 1
	s_add_i32 s99, s99, s98
	s_add_i32 s99, s99, 0x5fe
	s_lshr_b32 s100, s99, 3
	s_mul_i32 s101, s100, 0x5d2
	s_lshr_b32 s101, s101, 16
	s_mul_i32 vcc_lo, s101, 44
	s_sub_i32 s100, s100, vcc_lo
	s_and_b32 vcc_lo, s99, 7
	s_lshr_b32 vcc_hi, vcc_lo, 2
	s_lshl_b32 s101, s101, 1
	s_add_i32 s101, s101, vcc_hi
	s_and_b32 vcc_lo, vcc_lo, 3
	s_lshl_b32 s100, s100, 2
	s_add_i32 s100, s100, vcc_lo
	s_lshl_b32 s101, s101, 6
	s_lshl_b32 s100, s100, 6
	v_and_b32_e32 v66, 63, v1
	v_lshrrev_b32_e32 v67, 4, v66
	v_and_b32_e32 v68, 15, v66
	v_and_b32_e32 v73, 7, v66
	v_lshrrev_b32_e32 v72, 3, v66
	s_mul_i32 s99, s98, 0x4100
	v_mul_u32_u24_e32 v70, 0x104, v67
	v_lshl_add_u32 v70, v68, 4, v70
	v_add_u32_e32 v70, s99, v70
	v_mul_u32_u24_e32 v71, 0x820, v73
	v_lshl_add_u32 v71, v72, 2, v71
	v_add_u32_e32 v71, s99, v71
	s_mul_i32 s99, s101, 0x1600
	s_lshr_b32 vcc_lo, s100, 8
	s_lshl_b32 vcc_lo, vcc_lo, 7
	s_add_i32 s99, s99, vcc_lo
	s_and_b32 vcc_lo, s100, 0x7f
	s_add_i32 s99, s99, vcc_lo
	s_lshl_b32 s99, s99, 2
	v_mul_u32_u24_e32 v69, 0x5800, v67
	v_lshl_add_u32 v69, v68, 4, v69
	v_add_u32_e32 v69, s99, v69
	s_lshl_b32 s99, s100, 12
	s_lshl_b32 vcc_lo, s101, 1
	s_add_i32 s99, s99, vcc_lo
	v_lshlrev_b32_e32 v72, 12, v72
	v_lshl_add_u32 v72, v73, 4, v72
	v_add_u32_e32 v72, s99, v72
	s_lshl_b32 s99, s101, 2
	v_lshlrev_b32_e32 v73, 5, v73
	v_add_u32_e32 v73, s99, v73
	s_nop 0
	s_bitcmp1_b32 s100, 7
	v_readlane_b32 s100, v254, 6
	v_readlane_b32 s101, v254, 7
	v_readlane_b32 s98, v254, 8
	v_readlane_b32 s99, v254, 9
	s_nop 3
	s_cselect_b32 s100, s98, s100
	s_cselect_b32 s101, s99, s101
	v_readlane_b32 s98, v254, 4
	v_readlane_b32 s99, v254, 5
	global_load_dwordx4 v[2:5], v69, s[100:101] nt
	v_add_u32_e32 v68, 0x16000, v69
	global_load_dwordx4 v[6:9], v68, s[100:101] nt
	v_add_u32_e32 v67, 0x2c000, v69
	global_load_dwordx4 v[10:13], v67, s[100:101] nt
	v_add_u32_e32 v68, 0x42000, v69
	global_load_dwordx4 v[14:17], v68, s[100:101] nt
	v_add_u32_e32 v67, 0x58000, v69
	global_load_dwordx4 v[18:21], v67, s[100:101] nt
	v_add_u32_e32 v68, 0x6e000, v69
	global_load_dwordx4 v[22:25], v68, s[100:101] nt
	v_add_u32_e32 v67, 0x84000, v69
	global_load_dwordx4 v[26:29], v67, s[100:101] nt
	v_add_u32_e32 v68, 0x9a000, v69
	global_load_dwordx4 v[30:33], v68, s[100:101] nt
	v_add_u32_e32 v67, 0xb0000, v69
	global_load_dwordx4 v[34:37], v67, s[100:101] nt
	v_add_u32_e32 v68, 0xc6000, v69
	global_load_dwordx4 v[38:41], v68, s[100:101] nt
	v_add_u32_e32 v67, 0xdc000, v69
	global_load_dwordx4 v[42:45], v67, s[100:101] nt
	v_add_u32_e32 v68, 0xf2000, v69
	global_load_dwordx4 v[46:49], v68, s[100:101] nt
	v_add_u32_e32 v67, 0x108000, v69
	global_load_dwordx4 v[50:53], v67, s[100:101] nt
	v_add_u32_e32 v68, 0x11e000, v69
	global_load_dwordx4 v[54:57], v68, s[100:101] nt
	v_add_u32_e32 v67, 0x134000, v69
	global_load_dwordx4 v[58:61], v67, s[100:101] nt
	v_add_u32_e32 v68, 0x14a000, v69
	global_load_dwordx4 v[62:65], v68, s[100:101] nt
	global_load_dwordx4 v[74:77], v73, s[98:99]
	global_load_dwordx4 v[78:81], v73, s[98:99] offset:16
	s_waitcnt vmcnt(17)
	ds_write_b32 v70, v2
	ds_write_b32 v70, v3 offset:4
	ds_write_b32 v70, v4 offset:8
	ds_write_b32 v70, v5 offset:12
	s_waitcnt vmcnt(16)
	ds_write_b32 v70, v6 offset:1040
	ds_write_b32 v70, v7 offset:1044
	ds_write_b32 v70, v8 offset:1048
	ds_write_b32 v70, v9 offset:1052
	s_waitcnt vmcnt(15)
	ds_write_b32 v70, v10 offset:2080
	ds_write_b32 v70, v11 offset:2084
	ds_write_b32 v70, v12 offset:2088
	ds_write_b32 v70, v13 offset:2092
	s_waitcnt vmcnt(14)
	ds_write_b32 v70, v14 offset:3120
	ds_write_b32 v70, v15 offset:3124
	ds_write_b32 v70, v16 offset:3128
	ds_write_b32 v70, v17 offset:3132
	s_waitcnt vmcnt(13)
	ds_write_b32 v70, v18 offset:4160
	ds_write_b32 v70, v19 offset:4164
	ds_write_b32 v70, v20 offset:4168
	ds_write_b32 v70, v21 offset:4172
	s_waitcnt vmcnt(12)
	ds_write_b32 v70, v22 offset:5200
	ds_write_b32 v70, v23 offset:5204
	ds_write_b32 v70, v24 offset:5208
	ds_write_b32 v70, v25 offset:5212
	s_waitcnt vmcnt(11)
	ds_write_b32 v70, v26 offset:6240
	ds_write_b32 v70, v27 offset:6244
	ds_write_b32 v70, v28 offset:6248
	ds_write_b32 v70, v29 offset:6252
	s_waitcnt vmcnt(10)
	ds_write_b32 v70, v30 offset:7280
	ds_write_b32 v70, v31 offset:7284
	ds_write_b32 v70, v32 offset:7288
	ds_write_b32 v70, v33 offset:7292
	s_waitcnt vmcnt(9)
	ds_write_b32 v70, v34 offset:8320
	ds_write_b32 v70, v35 offset:8324
	ds_write_b32 v70, v36 offset:8328
	ds_write_b32 v70, v37 offset:8332
	s_waitcnt vmcnt(8)
	ds_write_b32 v70, v38 offset:9360
	ds_write_b32 v70, v39 offset:9364
	ds_write_b32 v70, v40 offset:9368
	ds_write_b32 v70, v41 offset:9372
	s_waitcnt vmcnt(7)
	ds_write_b32 v70, v42 offset:10400
	ds_write_b32 v70, v43 offset:10404
	ds_write_b32 v70, v44 offset:10408
	ds_write_b32 v70, v45 offset:10412
	s_waitcnt vmcnt(6)
	ds_write_b32 v70, v46 offset:11440
	ds_write_b32 v70, v47 offset:11444
	ds_write_b32 v70, v48 offset:11448
	ds_write_b32 v70, v49 offset:11452
	s_waitcnt vmcnt(5)
	ds_write_b32 v70, v50 offset:12480
	ds_write_b32 v70, v51 offset:12484
	ds_write_b32 v70, v52 offset:12488
	ds_write_b32 v70, v53 offset:12492
	s_waitcnt vmcnt(4)
	ds_write_b32 v70, v54 offset:13520
	ds_write_b32 v70, v55 offset:13524
	ds_write_b32 v70, v56 offset:13528
	ds_write_b32 v70, v57 offset:13532
	s_waitcnt vmcnt(3)
; #define LAS __attribute__((address_space(3)))
; __device__ __forceinline__ unsigned cvtpk(float lo, float hi) { f32x2_t v = {lo, hi}; bf16x2_t b = __builtin_convertvector(v, bf16x2_t); return __builtin_bit_cast(unsigned, b); }
; __device__ __forceinline__ void tr_all(const float* const* in, unsigned char* ws, LAS float* scr, int gw, int ngw, int lane, const TrRanges rg) {
;     ...
;         f32x4 g0 = {1.f, 1.f, 1.f, 1.f}, g1 = {1.f, 1.f, 1.f, 1.f};
;         if (cur.gain) { g0 = *(const f32x4*)cur.gain; g1 = *(const f32x4*)(cur.gain + 4); }
;         asm volatile("s_waitcnt lgkmcnt(0)" ::: "memory");
;         const LAS float* rp = scr + (8 * (lane & 7)) * 65 + (lane >> 3);
; #pragma unroll
;         for (int j = 0; j < 8; ++j) { const LAS float* s = rp + 8 * j;
;             u32x4 o; o.x = cvtpk(s[0 * 65] * g0[0], s[1 * 65] * g0[1]); o.y = cvtpk(s[2 * 65] * g0[2], s[3 * 65] * g0[3]);
;             o.z = cvtpk(s[4 * 65] * g1[0], s[5 * 65] * g1[1]); o.w = cvtpk(s[6 * 65] * g1[2], s[7 * 65] * g1[3]);
;             if (cur.nts) __builtin_nontemporal_store(o, (u32x4*)(cur.dst + (size_t)(8 * j) * cur.K)); else *(u32x4*)(cur.dst + (size_t)(8 * j) * cur.K) = o; }
	ds_write_b32 v70, v58 offset:14560
	ds_write_b32 v70, v59 offset:14564
	ds_write_b32 v70, v60 offset:14568
	ds_write_b32 v70, v61 offset:14572
	s_waitcnt vmcnt(2)
	ds_write_b32 v70, v62 offset:15600
	ds_write_b32 v70, v63 offset:15604
	ds_write_b32 v70, v64 offset:15608
	ds_write_b32 v70, v65 offset:15612
	s_add_u32 s100, s84, 0x8f00000
	s_addc_u32 s101, s85, 0
	s_waitcnt vmcnt(0) lgkmcnt(0)
	ds_read_b32 v2, v71
	ds_read_b32 v3, v71 offset:260
	ds_read_b32 v4, v71 offset:520
	ds_read_b32 v5, v71 offset:780
	ds_read_b32 v6, v71 offset:1040
	ds_read_b32 v7, v71 offset:1300
	ds_read_b32 v8, v71 offset:1560
	ds_read_b32 v9, v71 offset:1820
	ds_read_b32 v10, v71 offset:32
	ds_read_b32 v11, v71 offset:292
	ds_read_b32 v12, v71 offset:552
	ds_read_b32 v13, v71 offset:812
	ds_read_b32 v14, v71 offset:1072
	ds_read_b32 v15, v71 offset:1332
	ds_read_b32 v16, v71 offset:1592
	ds_read_b32 v17, v71 offset:1852
	ds_read_b32 v18, v71 offset:64
	ds_read_b32 v19, v71 offset:324
	ds_read_b32 v20, v71 offset:584
	ds_read_b32 v21, v71 offset:844
	ds_read_b32 v22, v71 offset:1104
	ds_read_b32 v23, v71 offset:1364
	ds_read_b32 v24, v71 offset:1624
	ds_read_b32 v25, v71 offset:1884
	ds_read_b32 v26, v71 offset:96
	ds_read_b32 v27, v71 offset:356
	ds_read_b32 v28, v71 offset:616
	ds_read_b32 v29, v71 offset:876
	ds_read_b32 v30, v71 offset:1136
	ds_read_b32 v31, v71 offset:1396
	ds_read_b32 v32, v71 offset:1656
	ds_read_b32 v33, v71 offset:1916
	ds_read_b32 v34, v71 offset:128
	ds_read_b32 v35, v71 offset:388
	ds_read_b32 v36, v71 offset:648
	ds_read_b32 v37, v71 offset:908
	ds_read_b32 v38, v71 offset:1168
	ds_read_b32 v39, v71 offset:1428
	ds_read_b32 v40, v71 offset:1688
	ds_read_b32 v41, v71 offset:1948
	ds_read_b32 v42, v71 offset:160
	ds_read_b32 v43, v71 offset:420
	ds_read_b32 v44, v71 offset:680
	ds_read_b32 v45, v71 offset:940
	ds_read_b32 v46, v71 offset:1200
	ds_read_b32 v47, v71 offset:1460
	ds_read_b32 v48, v71 offset:1720
	ds_read_b32 v49, v71 offset:1980
	ds_read_b32 v50, v71 offset:192
	ds_read_b32 v51, v71 offset:452
	ds_read_b32 v52, v71 offset:712
	ds_read_b32 v53, v71 offset:972
	ds_read_b32 v54, v71 offset:1232
	ds_read_b32 v55, v71 offset:1492
	ds_read_b32 v56, v71 offset:1752
	ds_read_b32 v57, v71 offset:2012
	ds_read_b32 v58, v71 offset:224
	ds_read_b32 v59, v71 offset:484
	ds_read_b32 v60, v71 offset:744
	ds_read_b32 v61, v71 offset:1004
	ds_read_b32 v62, v71 offset:1264
	ds_read_b32 v63, v71 offset:1524
	ds_read_b32 v64, v71 offset:1784
	ds_read_b32 v65, v71 offset:2044
	s_waitcnt lgkmcnt(15)
	v_mul_f32_e32 v2, v2, v74
	v_mul_f32_e32 v3, v3, v75
	v_mul_f32_e32 v4, v4, v76
	v_mul_f32_e32 v5, v5, v77
	v_mul_f32_e32 v6, v6, v78
	v_mul_f32_e32 v7, v7, v79
	v_mul_f32_e32 v8, v8, v80
	v_mul_f32_e32 v9, v9, v81
	v_cvt_pk_bf16_f32 v192, v2, v3
	v_cvt_pk_bf16_f32 v193, v4, v5
	v_cvt_pk_bf16_f32 v194, v6, v7
	v_cvt_pk_bf16_f32 v195, v8, v9
	global_store_dwordx4 v72, v[192:195], s[100:101] nt
	s_waitcnt lgkmcnt(15)
	v_mul_f32_e32 v10, v10, v74
	v_mul_f32_e32 v11, v11, v75
	v_mul_f32_e32 v12, v12, v76
	v_mul_f32_e32 v13, v13, v77
	v_mul_f32_e32 v14, v14, v78
	v_mul_f32_e32 v15, v15, v79
	v_mul_f32_e32 v16, v16, v80
	v_mul_f32_e32 v17, v17, v81
	v_cvt_pk_bf16_f32 v196, v10, v11
	v_cvt_pk_bf16_f32 v197, v12, v13
	v_cvt_pk_bf16_f32 v198, v14, v15
	v_cvt_pk_bf16_f32 v199, v16, v17
	v_add_u32_e32 v68, 0x8000, v72
	global_store_dwordx4 v68, v[196:199], s[100:101] nt
	s_waitcnt lgkmcnt(15)
	v_mul_f32_e32 v18, v18, v74
	v_mul_f32_e32 v19, v19, v75
	v_mul_f32_e32 v20, v20, v76
	v_mul_f32_e32 v21, v21, v77
	v_mul_f32_e32 v22, v22, v78
	v_mul_f32_e32 v23, v23, v79
	v_mul_f32_e32 v24, v24, v80
	v_mul_f32_e32 v25, v25, v81
	v_cvt_pk_bf16_f32 v200, v18, v19
	v_cvt_pk_bf16_f32 v201, v20, v21
	v_cvt_pk_bf16_f32 v202, v22, v23
	v_cvt_pk_bf16_f32 v203, v24, v25
	v_add_u32_e32 v67, 0x10000, v72
	global_store_dwordx4 v67, v[200:203], s[100:101] nt
	s_waitcnt lgkmcnt(15)
	v_mul_f32_e32 v26, v26, v74
	v_mul_f32_e32 v27, v27, v75
	v_mul_f32_e32 v28, v28, v76
	v_mul_f32_e32 v29, v29, v77
	v_mul_f32_e32 v30, v30, v78
	v_mul_f32_e32 v31, v31, v79
	v_mul_f32_e32 v32, v32, v80
	v_mul_f32_e32 v33, v33, v81
	v_cvt_pk_bf16_f32 v204, v26, v27
	v_cvt_pk_bf16_f32 v205, v28, v29
	v_cvt_pk_bf16_f32 v206, v30, v31
	v_cvt_pk_bf16_f32 v207, v32, v33
	v_add_u32_e32 v68, 0x18000, v72
	global_store_dwordx4 v68, v[204:207], s[100:101] nt
	s_waitcnt lgkmcnt(15)
	v_mul_f32_e32 v34, v34, v74
	v_mul_f32_e32 v35, v35, v75
	v_mul_f32_e32 v36, v36, v76
	v_mul_f32_e32 v37, v37, v77
	v_mul_f32_e32 v38, v38, v78
	v_mul_f32_e32 v39, v39, v79
	v_mul_f32_e32 v40, v40, v80
	v_mul_f32_e32 v41, v41, v81
	v_cvt_pk_bf16_f32 v208, v34, v35
	v_cvt_pk_bf16_f32 v209, v36, v37
	v_cvt_pk_bf16_f32 v210, v38, v39
	v_cvt_pk_bf16_f32 v211, v40, v41
	v_add_u32_e32 v67, 0x20000, v72
	global_store_dwordx4 v67, v[208:211], s[100:101] nt
	s_waitcnt lgkmcnt(15)
	v_mul_f32_e32 v42, v42, v74
	v_mul_f32_e32 v43, v43, v75
	v_mul_f32_e32 v44, v44, v76
	v_mul_f32_e32 v45, v45, v77
	v_mul_f32_e32 v46, v46, v78
	v_mul_f32_e32 v47, v47, v79
	v_mul_f32_e32 v48, v48, v80
	v_mul_f32_e32 v49, v49, v81
	v_cvt_pk_bf16_f32 v212, v42, v43
	v_cvt_pk_bf16_f32 v213, v44, v45
	v_cvt_pk_bf16_f32 v214, v46, v47
	v_cvt_pk_bf16_f32 v215, v48, v49
	v_add_u32_e32 v68, 0x28000, v72
	global_store_dwordx4 v68, v[212:215], s[100:101] nt
	s_waitcnt lgkmcnt(8)
	v_mul_f32_e32 v50, v50, v74
	v_mul_f32_e32 v51, v51, v75
	v_mul_f32_e32 v52, v52, v76
	v_mul_f32_e32 v53, v53, v77
	v_mul_f32_e32 v54, v54, v78
	v_mul_f32_e32 v55, v55, v79
	v_mul_f32_e32 v56, v56, v80
	v_mul_f32_e32 v57, v57, v81
	v_cvt_pk_bf16_f32 v216, v50, v51
	v_cvt_pk_bf16_f32 v217, v52, v53
	v_cvt_pk_bf16_f32 v218, v54, v55
	v_cvt_pk_bf16_f32 v219, v56, v57
	v_add_u32_e32 v67, 0x30000, v72
	global_store_dwordx4 v67, v[216:219], s[100:101] nt
	s_waitcnt lgkmcnt(0)
	v_mul_f32_e32 v58, v58, v74
	v_mul_f32_e32 v59, v59, v75
	v_mul_f32_e32 v60, v60, v76
	v_mul_f32_e32 v61, v61, v77
	v_mul_f32_e32 v62, v62, v78
	v_mul_f32_e32 v63, v63, v79
	v_mul_f32_e32 v64, v64, v80
	v_mul_f32_e32 v65, v65, v81
	v_cvt_pk_bf16_f32 v220, v58, v59
	v_cvt_pk_bf16_f32 v221, v60, v61
	v_cvt_pk_bf16_f32 v222, v62, v63
	v_cvt_pk_bf16_f32 v223, v64, v65
	v_add_u32_e32 v68, 0x38000, v72
	global_store_dwordx4 v68, v[220:223], s[100:101] nt

; #define LAS __attribute__((address_space(3)))
; #define TR_LOAD(p) __builtin_nontemporal_load(p)
; __device__ __forceinline__ TrItem tr_decode(int it, const float* const* in, unsigned char* ws, int lane) {
;     ...
;     const int rh = r >> 3, rl = r & 7, nq = ndb >> DL, kbh = rh / nq, dbh = rh - kbh * nq;
;     const int kb = (kbh << KL) + (rl >> DL), db = (dbh << DL) + (rl & ((1 << DL) - 1)), d0 = db * 64, k0 = kb * 64;
;     ...
;     const int kb = r / ndb, db = r - kb * ndb, d0 = db * 64, k0 = kb * 64;
;     ...
;     const int blk = d0 + 32 * ((lane & 15) >> 3);
;     const float* src = W; int s0 = blk;
;     if (kind == 1) { const int pn = blk >> 8, bj = (blk >> 7) & 1, o = blk & 127; src = bj ? W2 : W; s0 = pn * 128 + o; }
;     else if (kind == 2) s0 = win_src(blk);
;     TrItem t; t.src = src + (size_t)(k0 + (lane >> 4)) * N + s0 + 4 * (lane & 7); t.gain = gain ? gain + k0 + 8 * (lane & 7) : nullptr;
;     t.dst = WT + (size_t)(d0 + (lane >> 3)) * K + k0 + 8 * (lane & 7); t.N = N; t.K = K; t.nts = nts && TR_NTS;
; __device__ __forceinline__ void tr_all(const float* const* in, unsigned char* ws, LAS float* scr, int gw, int ngw, int lane, const TrRanges rg) {
;     ...
;     for (int i = 0; i < 16; ++i) v[i] = TR_LOAD((const f32x4*)(cur.src + (size_t)(4 * i) * cur.N));
;     for (int it = gw; it < TR_CNT; it += ngw) {
;         const int nit = it + ngw; const bool hn = nit < TR_CNT;
;         TrItem nx = cur; f32x4 w[16];
;         if (hn) { nx = tr_decode(rg.item(nit), in, ws, lane);
; #pragma unroll
;             for (int i = 0; i < 16; ++i) w[i] = TR_LOAD((const f32x4*)(nx.src + (size_t)(4 * i) * nx.N)); }
;         LAS float* wp = scr + (lane >> 4) * 65 + 4 * (lane & 15);
; #pragma unroll
;         for (int i = 0; i < 16; ++i) { wp[(4 * i) * 65 + 0] = v[i][0]; wp[(4 * i) * 65 + 1] = v[i][1]; wp[(4 * i) * 65 + 2] = v[i][2]; wp[(4 * i) * 65 + 3] = v[i][3]; }
.Lseam_cv_1:
	s_cmp_lt_u32 s98, 2
	s_cbranch_scc1 .LBB0_570
	s_cmp_gt_u32 s98, 3
	s_cbranch_scc1 .LBB0_570
	s_mov_b64 exec, -1
	s_lshl_b32 s99, s87, 1
	s_add_i32 s99, s99, s98
	s_add_i32 s99, s99, 0x7fe
	s_lshr_b32 s100, s99, 3
	s_mul_i32 s101, s100, 0x5d2
	s_lshr_b32 s101, s101, 16
	s_mul_i32 vcc_lo, s101, 44
	s_sub_i32 s100, s100, vcc_lo
	s_and_b32 vcc_lo, s99, 7
	s_lshr_b32 vcc_hi, vcc_lo, 2
	s_lshl_b32 s101, s101, 1
	s_add_i32 s101, s101, vcc_hi
	s_and_b32 vcc_lo, vcc_lo, 3
	s_lshl_b32 s100, s100, 2
	s_add_i32 s100, s100, vcc_lo
	s_lshl_b32 s101, s101, 6
	s_lshl_b32 s100, s100, 6
	v_and_b32_e32 v66, 63, v1
	v_lshrrev_b32_e32 v67, 4, v66
	v_and_b32_e32 v68, 15, v66
	v_and_b32_e32 v73, 7, v66
	v_lshrrev_b32_e32 v72, 3, v66
	s_mul_i32 s99, s98, 0x4100
	v_mul_u32_u24_e32 v70, 0x104, v67
	v_lshl_add_u32 v70, v68, 4, v70
	v_add_u32_e32 v70, s99, v70
	v_mul_u32_u24_e32 v71, 0x820, v73
	v_lshl_add_u32 v71, v72, 2, v71
	v_add_u32_e32 v71, s99, v71
	s_mul_i32 s99, s101, 0x1600
	s_lshr_b32 vcc_lo, s100, 8
	s_lshl_b32 vcc_lo, vcc_lo, 7
	s_add_i32 s99, s99, vcc_lo
	s_and_b32 vcc_lo, s100, 0x7f
	s_add_i32 s99, s99, vcc_lo
	s_lshl_b32 s99, s99, 2
	v_mul_u32_u24_e32 v69, 0x5800, v67
	v_lshl_add_u32 v69, v68, 4, v69
	v_add_u32_e32 v69, s99, v69
	s_lshl_b32 s99, s100, 12
	s_lshl_b32 vcc_lo, s101, 1
	s_add_i32 s99, s99, vcc_lo
	v_lshlrev_b32_e32 v72, 12, v72
	v_lshl_add_u32 v72, v73, 4, v72
	v_add_u32_e32 v72, s99, v72
	s_lshl_b32 s99, s101, 2
	v_lshlrev_b32_e32 v73, 5, v73
	v_add_u32_e32 v73, s99, v73
	s_nop 0
	s_bitcmp1_b32 s100, 7
	v_readlane_b32 s100, v254, 6
	v_readlane_b32 s101, v254, 7
	v_readlane_b32 s98, v254, 8
	v_readlane_b32 s99, v254, 9
	s_nop 3
	s_cselect_b32 s100, s98, s100
	s_cselect_b32 s101, s99, s101
	v_readlane_b32 s98, v254, 4
	v_readlane_b32 s99, v254, 5
	global_load_dwordx4 v[2:5], v69, s[100:101] nt
	v_add_u32_e32 v68, 0x16000, v69
	global_load_dwordx4 v[6:9], v68, s[100:101] nt
	v_add_u32_e32 v67, 0x2c000, v69
	global_load_dwordx4 v[10:13], v67, s[100:101] nt
	v_add_u32_e32 v68, 0x42000, v69
	global_load_dwordx4 v[14:17], v68, s[100:101] nt
	v_add_u32_e32 v67, 0x58000, v69
	global_load_dwordx4 v[18:21], v67, s[100:101] nt
	v_add_u32_e32 v68, 0x6e000, v69
	global_load_dwordx4 v[22:25], v68, s[100:101] nt
	v_add_u32_e32 v67, 0x84000, v69
	global_load_dwordx4 v[26:29], v67, s[100:101] nt
	v_add_u32_e32 v68, 0x9a000, v69
	global_load_dwordx4 v[30:33], v68, s[100:101] nt
	v_add_u32_e32 v67, 0xb0000, v69
	global_load_dwordx4 v[34:37], v67, s[100:101] nt
	v_add_u32_e32 v68, 0xc6000, v69
	global_load_dwordx4 v[38:41], v68, s[100:101] nt
	v_add_u32_e32 v67, 0xdc000, v69
	global_load_dwordx4 v[42:45], v67, s[100:101] nt
	v_add_u32_e32 v68, 0xf2000, v69
	global_load_dwordx4 v[46:49], v68, s[100:101] nt
	v_add_u32_e32 v67, 0x108000, v69
	global_load_dwordx4 v[50:53], v67, s[100:101] nt
	v_add_u32_e32 v68, 0x11e000, v69
	global_load_dwordx4 v[54:57], v68, s[100:101] nt
	v_add_u32_e32 v67, 0x134000, v69
	global_load_dwordx4 v[58:61], v67, s[100:101] nt
	v_add_u32_e32 v68, 0x14a000, v69
	global_load_dwordx4 v[62:65], v68, s[100:101] nt
	global_load_dwordx4 v[74:77], v73, s[98:99]
	global_load_dwordx4 v[78:81], v73, s[98:99] offset:16
	s_waitcnt vmcnt(17)
	ds_write_b32 v70, v2
	ds_write_b32 v70, v3 offset:4
	ds_write_b32 v70, v4 offset:8
	ds_write_b32 v70, v5 offset:12
	s_waitcnt vmcnt(16)
	ds_write_b32 v70, v6 offset:1040
	ds_write_b32 v70, v7 offset:1044
	ds_write_b32 v70, v8 offset:1048
	ds_write_b32 v70, v9 offset:1052
	s_waitcnt vmcnt(15)
	ds_write_b32 v70, v10 offset:2080
	ds_write_b32 v70, v11 offset:2084
	ds_write_b32 v70, v12 offset:2088
	ds_write_b32 v70, v13 offset:2092
	s_waitcnt vmcnt(14)
	ds_write_b32 v70, v14 offset:3120
	ds_write_b32 v70, v15 offset:3124
	ds_write_b32 v70, v16 offset:3128
	ds_write_b32 v70, v17 offset:3132
	s_waitcnt vmcnt(13)
	ds_write_b32 v70, v18 offset:4160
	ds_write_b32 v70, v19 offset:4164
	ds_write_b32 v70, v20 offset:4168
	ds_write_b32 v70, v21 offset:4172
	s_waitcnt vmcnt(12)
	ds_write_b32 v70, v22 offset:5200
	ds_write_b32 v70, v23 offset:5204
	ds_write_b32 v70, v24 offset:5208
	ds_write_b32 v70, v25 offset:5212
	s_waitcnt vmcnt(11)
	ds_write_b32 v70, v26 offset:6240
	ds_write_b32 v70, v27 offset:6244
	ds_write_b32 v70, v28 offset:6248
	ds_write_b32 v70, v29 offset:6252
	s_waitcnt vmcnt(10)
	ds_write_b32 v70, v30 offset:7280
	ds_write_b32 v70, v31 offset:7284
	ds_write_b32 v70, v32 offset:7288
	ds_write_b32 v70, v33 offset:7292
	s_waitcnt vmcnt(9)
	ds_write_b32 v70, v34 offset:8320
	ds_write_b32 v70, v35 offset:8324
	ds_write_b32 v70, v36 offset:8328
	ds_write_b32 v70, v37 offset:8332
	s_waitcnt vmcnt(8)
	ds_write_b32 v70, v38 offset:9360
	ds_write_b32 v70, v39 offset:9364
	ds_write_b32 v70, v40 offset:9368
	ds_write_b32 v70, v41 offset:9372
	s_waitcnt vmcnt(7)
	ds_write_b32 v70, v42 offset:10400
	ds_write_b32 v70, v43 offset:10404
	ds_write_b32 v70, v44 offset:10408
	ds_write_b32 v70, v45 offset:10412
	s_waitcnt vmcnt(6)
	ds_write_b32 v70, v46 offset:11440
	ds_write_b32 v70, v47 offset:11444
	ds_write_b32 v70, v48 offset:11448
	ds_write_b32 v70, v49 offset:11452
	s_waitcnt vmcnt(5)
	ds_write_b32 v70, v50 offset:12480
	ds_write_b32 v70, v51 offset:12484
	ds_write_b32 v70, v52 offset:12488
	ds_write_b32 v70, v53 offset:12492
	s_waitcnt vmcnt(4)
	ds_write_b32 v70, v54 offset:13520
	ds_write_b32 v70, v55 offset:13524
	ds_write_b32 v70, v56 offset:13528
	ds_write_b32 v70, v57 offset:13532
	s_waitcnt vmcnt(3)
	ds_write_b32 v70, v58 offset:14560
	ds_write_b32 v70, v59 offset:14564
	ds_write_b32 v70, v60 offset:14568
	ds_write_b32 v70, v61 offset:14572
	s_waitcnt vmcnt(2)
; #define LAS __attribute__((address_space(3)))
; __device__ __forceinline__ unsigned cvtpk(float lo, float hi) { f32x2_t v = {lo, hi}; bf16x2_t b = __builtin_convertvector(v, bf16x2_t); return __builtin_bit_cast(unsigned, b); }
; __device__ __forceinline__ void tr_all(const float* const* in, unsigned char* ws, LAS float* scr, int gw, int ngw, int lane, const TrRanges rg) {
;     ...
;         f32x4 g0 = {1.f, 1.f, 1.f, 1.f}, g1 = {1.f, 1.f, 1.f, 1.f};
;         if (cur.gain) { g0 = *(const f32x4*)cur.gain; g1 = *(const f32x4*)(cur.gain + 4); }
;         asm volatile("s_waitcnt lgkmcnt(0)" ::: "memory");
;         const LAS float* rp = scr + (8 * (lane & 7)) * 65 + (lane >> 3);
; #pragma unroll
;         for (int j = 0; j < 8; ++j) { const LAS float* s = rp + 8 * j;
;             u32x4 o; o.x = cvtpk(s[0 * 65] * g0[0], s[1 * 65] * g0[1]); o.y = cvtpk(s[2 * 65] * g0[2], s[3 * 65] * g0[3]);
;             o.z = cvtpk(s[4 * 65] * g1[0], s[5 * 65] * g1[1]); o.w = cvtpk(s[6 * 65] * g1[2], s[7 * 65] * g1[3]);
;             if (cur.nts) __builtin_nontemporal_store(o, (u32x4*)(cur.dst + (size_t)(8 * j) * cur.K)); else *(u32x4*)(cur.dst + (size_t)(8 * j) * cur.K) = o; }
	ds_write_b32 v70, v62 offset:15600
	ds_write_b32 v70, v63 offset:15604
	ds_write_b32 v70, v64 offset:15608
	ds_write_b32 v70, v65 offset:15612
	s_add_u32 s100, s84, 0x8f00000
	s_addc_u32 s101, s85, 0
	s_waitcnt vmcnt(0) lgkmcnt(0)
	ds_read_b32 v2, v71
	ds_read_b32 v3, v71 offset:260
	ds_read_b32 v4, v71 offset:520
	ds_read_b32 v5, v71 offset:780
	ds_read_b32 v6, v71 offset:1040
	ds_read_b32 v7, v71 offset:1300
	ds_read_b32 v8, v71 offset:1560
	ds_read_b32 v9, v71 offset:1820
	ds_read_b32 v10, v71 offset:32
	ds_read_b32 v11, v71 offset:292
	ds_read_b32 v12, v71 offset:552
	ds_read_b32 v13, v71 offset:812
	ds_read_b32 v14, v71 offset:1072
	ds_read_b32 v15, v71 offset:1332
	ds_read_b32 v16, v71 offset:1592
	ds_read_b32 v17, v71 offset:1852
	ds_read_b32 v18, v71 offset:64
	ds_read_b32 v19, v71 offset:324
	ds_read_b32 v20, v71 offset:584
	ds_read_b32 v21, v71 offset:844
	ds_read_b32 v22, v71 offset:1104
	ds_read_b32 v23, v71 offset:1364
	ds_read_b32 v24, v71 offset:1624
	ds_read_b32 v25, v71 offset:1884
	ds_read_b32 v26, v71 offset:96
	ds_read_b32 v27, v71 offset:356
	ds_read_b32 v28, v71 offset:616
	ds_read_b32 v29, v71 offset:876
	ds_read_b32 v30, v71 offset:1136
	ds_read_b32 v31, v71 offset:1396
	ds_read_b32 v32, v71 offset:1656
	ds_read_b32 v33, v71 offset:1916
	ds_read_b32 v34, v71 offset:128
	ds_read_b32 v35, v71 offset:388
	ds_read_b32 v36, v71 offset:648
	ds_read_b32 v37, v71 offset:908
	ds_read_b32 v38, v71 offset:1168
	ds_read_b32 v39, v71 offset:1428
	ds_read_b32 v40, v71 offset:1688
	ds_read_b32 v41, v71 offset:1948
	ds_read_b32 v42, v71 offset:160
	ds_read_b32 v43, v71 offset:420
	ds_read_b32 v44, v71 offset:680
	ds_read_b32 v45, v71 offset:940
	ds_read_b32 v46, v71 offset:1200
	ds_read_b32 v47, v71 offset:1460
	ds_read_b32 v48, v71 offset:1720
	ds_read_b32 v49, v71 offset:1980
	ds_read_b32 v50, v71 offset:192
	ds_read_b32 v51, v71 offset:452
	ds_read_b32 v52, v71 offset:712
	ds_read_b32 v53, v71 offset:972
	ds_read_b32 v54, v71 offset:1232
	ds_read_b32 v55, v71 offset:1492
	ds_read_b32 v56, v71 offset:1752
	ds_read_b32 v57, v71 offset:2012
	ds_read_b32 v58, v71 offset:224
	ds_read_b32 v59, v71 offset:484
	ds_read_b32 v60, v71 offset:744
	ds_read_b32 v61, v71 offset:1004
	ds_read_b32 v62, v71 offset:1264
	ds_read_b32 v63, v71 offset:1524
	ds_read_b32 v64, v71 offset:1784
	ds_read_b32 v65, v71 offset:2044
	s_waitcnt lgkmcnt(15)
	v_mul_f32_e32 v2, v2, v74
	v_mul_f32_e32 v3, v3, v75
	v_mul_f32_e32 v4, v4, v76
	v_mul_f32_e32 v5, v5, v77
	v_mul_f32_e32 v6, v6, v78
	v_mul_f32_e32 v7, v7, v79
	v_mul_f32_e32 v8, v8, v80
	v_mul_f32_e32 v9, v9, v81
	v_cvt_pk_bf16_f32 v192, v2, v3
	v_cvt_pk_bf16_f32 v193, v4, v5
	v_cvt_pk_bf16_f32 v194, v6, v7
	v_cvt_pk_bf16_f32 v195, v8, v9
	global_store_dwordx4 v72, v[192:195], s[100:101] nt
	s_waitcnt lgkmcnt(15)
	v_mul_f32_e32 v10, v10, v74
	v_mul_f32_e32 v11, v11, v75
	v_mul_f32_e32 v12, v12, v76
	v_mul_f32_e32 v13, v13, v77
	v_mul_f32_e32 v14, v14, v78
	v_mul_f32_e32 v15, v15, v79
	v_mul_f32_e32 v16, v16, v80
	v_mul_f32_e32 v17, v17, v81
	v_cvt_pk_bf16_f32 v196, v10, v11
	v_cvt_pk_bf16_f32 v197, v12, v13
	v_cvt_pk_bf16_f32 v198, v14, v15
	v_cvt_pk_bf16_f32 v199, v16, v17
	v_add_u32_e32 v68, 0x8000, v72
	global_store_dwordx4 v68, v[196:199], s[100:101] nt
	s_waitcnt lgkmcnt(15)
	v_mul_f32_e32 v18, v18, v74
	v_mul_f32_e32 v19, v19, v75
	v_mul_f32_e32 v20, v20, v76
	v_mul_f32_e32 v21, v21, v77
	v_mul_f32_e32 v22, v22, v78
	v_mul_f32_e32 v23, v23, v79
	v_mul_f32_e32 v24, v24, v80
	v_mul_f32_e32 v25, v25, v81
	v_cvt_pk_bf16_f32 v200, v18, v19
	v_cvt_pk_bf16_f32 v201, v20, v21
	v_cvt_pk_bf16_f32 v202, v22, v23
	v_cvt_pk_bf16_f32 v203, v24, v25
	v_add_u32_e32 v67, 0x10000, v72
	global_store_dwordx4 v67, v[200:203], s[100:101] nt
	s_waitcnt lgkmcnt(15)
	v_mul_f32_e32 v26, v26, v74
	v_mul_f32_e32 v27, v27, v75
	v_mul_f32_e32 v28, v28, v76
	v_mul_f32_e32 v29, v29, v77
	v_mul_f32_e32 v30, v30, v78
	v_mul_f32_e32 v31, v31, v79
	v_mul_f32_e32 v32, v32, v80
	v_mul_f32_e32 v33, v33, v81
	v_cvt_pk_bf16_f32 v204, v26, v27
	v_cvt_pk_bf16_f32 v205, v28, v29
	v_cvt_pk_bf16_f32 v206, v30, v31
	v_cvt_pk_bf16_f32 v207, v32, v33
	v_add_u32_e32 v68, 0x18000, v72
	global_store_dwordx4 v68, v[204:207], s[100:101] nt
	s_waitcnt lgkmcnt(15)
	v_mul_f32_e32 v34, v34, v74
	v_mul_f32_e32 v35, v35, v75
	v_mul_f32_e32 v36, v36, v76
	v_mul_f32_e32 v37, v37, v77
	v_mul_f32_e32 v38, v38, v78
	v_mul_f32_e32 v39, v39, v79
	v_mul_f32_e32 v40, v40, v80
	v_mul_f32_e32 v41, v41, v81
	v_cvt_pk_bf16_f32 v208, v34, v35
	v_cvt_pk_bf16_f32 v209, v36, v37
	v_cvt_pk_bf16_f32 v210, v38, v39
	v_cvt_pk_bf16_f32 v211, v40, v41
	v_add_u32_e32 v67, 0x20000, v72
	global_store_dwordx4 v67, v[208:211], s[100:101] nt
	s_waitcnt lgkmcnt(15)
	v_mul_f32_e32 v42, v42, v74
	v_mul_f32_e32 v43, v43, v75
	v_mul_f32_e32 v44, v44, v76
	v_mul_f32_e32 v45, v45, v77
	v_mul_f32_e32 v46, v46, v78
	v_mul_f32_e32 v47, v47, v79
	v_mul_f32_e32 v48, v48, v80
	v_mul_f32_e32 v49, v49, v81
	v_cvt_pk_bf16_f32 v212, v42, v43
	v_cvt_pk_bf16_f32 v213, v44, v45
	v_cvt_pk_bf16_f32 v214, v46, v47
	v_cvt_pk_bf16_f32 v215, v48, v49
	v_add_u32_e32 v68, 0x28000, v72
	global_store_dwordx4 v68, v[212:215], s[100:101] nt
	s_waitcnt lgkmcnt(8)
	v_mul_f32_e32 v50, v50, v74
	v_mul_f32_e32 v51, v51, v75
	v_mul_f32_e32 v52, v52, v76
	v_mul_f32_e32 v53, v53, v77
	v_mul_f32_e32 v54, v54, v78
	v_mul_f32_e32 v55, v55, v79
	v_mul_f32_e32 v56, v56, v80
	v_mul_f32_e32 v57, v57, v81
	v_cvt_pk_bf16_f32 v216, v50, v51
	v_cvt_pk_bf16_f32 v217, v52, v53
	v_cvt_pk_bf16_f32 v218, v54, v55
	v_cvt_pk_bf16_f32 v219, v56, v57
	v_add_u32_e32 v67, 0x30000, v72
	global_store_dwordx4 v67, v[216:219], s[100:101] nt
	s_waitcnt lgkmcnt(0)
	v_mul_f32_e32 v58, v58, v74
	v_mul_f32_e32 v59, v59, v75
	v_mul_f32_e32 v60, v60, v76
	v_mul_f32_e32 v61, v61, v77
	v_mul_f32_e32 v62, v62, v78
	v_mul_f32_e32 v63, v63, v79
	v_mul_f32_e32 v64, v64, v80
	v_mul_f32_e32 v65, v65, v81
	v_cvt_pk_bf16_f32 v220, v58, v59
	v_cvt_pk_bf16_f32 v221, v60, v61
	v_cvt_pk_bf16_f32 v222, v62, v63
	v_cvt_pk_bf16_f32 v223, v64, v65
	v_add_u32_e32 v68, 0x38000, v72
	global_store_dwordx4 v68, v[220:223], s[100:101] nt

; #define LAS __attribute__((address_space(3)))
; #define TR_LOAD(p) __builtin_nontemporal_load(p)
; __device__ __forceinline__ TrItem tr_decode(int it, const float* const* in, unsigned char* ws, int lane) {
;     ...
;     const int rh = r >> 3, rl = r & 7, nq = ndb >> DL, kbh = rh / nq, dbh = rh - kbh * nq;
;     const int kb = (kbh << KL) + (rl >> DL), db = (dbh << DL) + (rl & ((1 << DL) - 1)), d0 = db * 64, k0 = kb * 64;
;     ...
;     const int kb = r / ndb, db = r - kb * ndb, d0 = db * 64, k0 = kb * 64;
;     ...
;     const int blk = d0 + 32 * ((lane & 15) >> 3);
;     const float* src = W; int s0 = blk;
;     if (kind == 1) { const int pn = blk >> 8, bj = (blk >> 7) & 1, o = blk & 127; src = bj ? W2 : W; s0 = pn * 128 + o; }
;     else if (kind == 2) s0 = win_src(blk);
;     TrItem t; t.src = src + (size_t)(k0 + (lane >> 4)) * N + s0 + 4 * (lane & 7); t.gain = gain ? gain + k0 + 8 * (lane & 7) : nullptr;
;     t.dst = WT + (size_t)(d0 + (lane >> 3)) * K + k0 + 8 * (lane & 7); t.N = N; t.K = K; t.nts = nts && TR_NTS;
; __device__ __forceinline__ void tr_all(const float* const* in, unsigned char* ws, LAS float* scr, int gw, int ngw, int lane, const TrRanges rg) {
;     ...
;     for (int i = 0; i < 16; ++i) v[i] = TR_LOAD((const f32x4*)(cur.src + (size_t)(4 * i) * cur.N));
;     for (int it = gw; it < TR_CNT; it += ngw) {
;         const int nit = it + ngw; const bool hn = nit < TR_CNT;
;         TrItem nx = cur; f32x4 w[16];
;         if (hn) { nx = tr_decode(rg.item(nit), in, ws, lane);
; #pragma unroll
;             for (int i = 0; i < 16; ++i) w[i] = TR_LOAD((const f32x4*)(nx.src + (size_t)(4 * i) * nx.N)); }
;         LAS float* wp = scr + (lane >> 4) * 65 + 4 * (lane & 15);
; #pragma unroll
;         for (int i = 0; i < 16; ++i) { wp[(4 * i) * 65 + 0] = v[i][0]; wp[(4 * i) * 65 + 1] = v[i][1]; wp[(4 * i) * 65 + 2] = v[i][2]; wp[(4 * i) * 65 + 3] = v[i][3]; }
.Lseam_cv_2:
	s_cmp_lt_u32 s98, 2
	s_cbranch_scc1 .LBB0_681
	s_cmp_gt_u32 s98, 3
	s_cbranch_scc1 .LBB0_681
	s_mov_b64 exec, -1
	s_lshl_b32 s99, s87, 1
	s_add_i32 s99, s99, s98
	s_add_i32 s99, s99, 0x9fe
	s_lshr_b32 s100, s99, 3
	s_mul_i32 s101, s100, 0x5d2
	s_lshr_b32 s101, s101, 16
	s_mul_i32 vcc_lo, s101, 44
	s_sub_i32 s100, s100, vcc_lo
	s_and_b32 vcc_lo, s99, 7
	s_lshr_b32 vcc_hi, vcc_lo, 2
	s_lshl_b32 s101, s101, 1
	s_add_i32 s101, s101, vcc_hi
	s_and_b32 vcc_lo, vcc_lo, 3
	s_lshl_b32 s100, s100, 2
	s_add_i32 s100, s100, vcc_lo
	s_lshl_b32 s101, s101, 6
	s_lshl_b32 s100, s100, 6
	v_and_b32_e32 v66, 63, v1
	v_lshrrev_b32_e32 v67, 4, v66
	v_and_b32_e32 v68, 15, v66
	v_and_b32_e32 v73, 7, v66
	v_lshrrev_b32_e32 v72, 3, v66
	s_mul_i32 s99, s98, 0x4100
	v_mul_u32_u24_e32 v70, 0x104, v67
	v_lshl_add_u32 v70, v68, 4, v70
	v_add_u32_e32 v70, s99, v70
	v_mul_u32_u24_e32 v71, 0x820, v73
	v_lshl_add_u32 v71, v72, 2, v71
	v_add_u32_e32 v71, s99, v71
	s_mul_i32 s99, s101, 0x1600
	s_lshr_b32 vcc_lo, s100, 8
	s_lshl_b32 vcc_lo, vcc_lo, 7
	s_add_i32 s99, s99, vcc_lo
	s_and_b32 vcc_lo, s100, 0x7f
	s_add_i32 s99, s99, vcc_lo
	s_lshl_b32 s99, s99, 2
	v_mul_u32_u24_e32 v69, 0x5800, v67
	v_lshl_add_u32 v69, v68, 4, v69
	v_add_u32_e32 v69, s99, v69
	s_lshl_b32 s99, s100, 12
	s_lshl_b32 vcc_lo, s101, 1
	s_add_i32 s99, s99, vcc_lo
	v_lshlrev_b32_e32 v72, 12, v72
	v_lshl_add_u32 v72, v73, 4, v72
	v_add_u32_e32 v72, s99, v72
	s_lshl_b32 s99, s101, 2
	v_lshlrev_b32_e32 v73, 5, v73
	v_add_u32_e32 v73, s99, v73
	s_nop 0
	s_bitcmp1_b32 s100, 7
	v_readlane_b32 s100, v254, 6
	v_readlane_b32 s101, v254, 7
	v_readlane_b32 s98, v254, 8
	v_readlane_b32 s99, v254, 9
	s_nop 3
	s_cselect_b32 s100, s98, s100
	s_cselect_b32 s101, s99, s101
	v_readlane_b32 s98, v254, 4
	v_readlane_b32 s99, v254, 5
	global_load_dwordx4 v[2:5], v69, s[100:101] nt
	v_add_u32_e32 v68, 0x16000, v69
	global_load_dwordx4 v[6:9], v68, s[100:101] nt
	v_add_u32_e32 v67, 0x2c000, v69
	global_load_dwordx4 v[10:13], v67, s[100:101] nt
	v_add_u32_e32 v68, 0x42000, v69
	global_load_dwordx4 v[14:17], v68, s[100:101] nt
	v_add_u32_e32 v67, 0x58000, v69
	global_load_dwordx4 v[18:21], v67, s[100:101] nt
	v_add_u32_e32 v68, 0x6e000, v69
	global_load_dwordx4 v[22:25], v68, s[100:101] nt
	v_add_u32_e32 v67, 0x84000, v69
	global_load_dwordx4 v[26:29], v67, s[100:101] nt
	v_add_u32_e32 v68, 0x9a000, v69
	global_load_dwordx4 v[30:33], v68, s[100:101] nt
	v_add_u32_e32 v67, 0xb0000, v69
	global_load_dwordx4 v[34:37], v67, s[100:101] nt
	v_add_u32_e32 v68, 0xc6000, v69
	global_load_dwordx4 v[38:41], v68, s[100:101] nt
	v_add_u32_e32 v67, 0xdc000, v69
	global_load_dwordx4 v[42:45], v67, s[100:101] nt
	v_add_u32_e32 v68, 0xf2000, v69
	global_load_dwordx4 v[46:49], v68, s[100:101] nt
	v_add_u32_e32 v67, 0x108000, v69
	global_load_dwordx4 v[50:53], v67, s[100:101] nt
	v_add_u32_e32 v68, 0x11e000, v69
	global_load_dwordx4 v[54:57], v68, s[100:101] nt
	v_add_u32_e32 v67, 0x134000, v69
	global_load_dwordx4 v[58:61], v67, s[100:101] nt
	v_add_u32_e32 v68, 0x14a000, v69
	global_load_dwordx4 v[62:65], v68, s[100:101] nt
	global_load_dwordx4 v[74:77], v73, s[98:99]
	global_load_dwordx4 v[78:81], v73, s[98:99] offset:16
	s_waitcnt vmcnt(17)
	ds_write_b32 v70, v2
	ds_write_b32 v70, v3 offset:4
	ds_write_b32 v70, v4 offset:8
	ds_write_b32 v70, v5 offset:12
	s_waitcnt vmcnt(16)
	ds_write_b32 v70, v6 offset:1040
	ds_write_b32 v70, v7 offset:1044
	ds_write_b32 v70, v8 offset:1048
	ds_write_b32 v70, v9 offset:1052
	s_waitcnt vmcnt(15)
	ds_write_b32 v70, v10 offset:2080
	ds_write_b32 v70, v11 offset:2084
	ds_write_b32 v70, v12 offset:2088
	ds_write_b32 v70, v13 offset:2092
	s_waitcnt vmcnt(14)
	ds_write_b32 v70, v14 offset:3120
	ds_write_b32 v70, v15 offset:3124
	ds_write_b32 v70, v16 offset:3128
	ds_write_b32 v70, v17 offset:3132
	s_waitcnt vmcnt(13)
	ds_write_b32 v70, v18 offset:4160
	ds_write_b32 v70, v19 offset:4164
	ds_write_b32 v70, v20 offset:4168
	ds_write_b32 v70, v21 offset:4172
	s_waitcnt vmcnt(12)
	ds_write_b32 v70, v22 offset:5200
	ds_write_b32 v70, v23 offset:5204
	ds_write_b32 v70, v24 offset:5208
	ds_write_b32 v70, v25 offset:5212
	s_waitcnt vmcnt(11)
	ds_write_b32 v70, v26 offset:6240
	ds_write_b32 v70, v27 offset:6244
	ds_write_b32 v70, v28 offset:6248
	ds_write_b32 v70, v29 offset:6252
	s_waitcnt vmcnt(10)
	ds_write_b32 v70, v30 offset:7280
	ds_write_b32 v70, v31 offset:7284
	ds_write_b32 v70, v32 offset:7288
	ds_write_b32 v70, v33 offset:7292
	s_waitcnt vmcnt(9)
	ds_write_b32 v70, v34 offset:8320
	ds_write_b32 v70, v35 offset:8324
	ds_write_b32 v70, v36 offset:8328
	ds_write_b32 v70, v37 offset:8332
	s_waitcnt vmcnt(8)
	ds_write_b32 v70, v38 offset:9360
	ds_write_b32 v70, v39 offset:9364
	ds_write_b32 v70, v40 offset:9368
	ds_write_b32 v70, v41 offset:9372
	s_waitcnt vmcnt(7)
	ds_write_b32 v70, v42 offset:10400
	ds_write_b32 v70, v43 offset:10404
	ds_write_b32 v70, v44 offset:10408
	ds_write_b32 v70, v45 offset:10412
	s_waitcnt vmcnt(6)
	ds_write_b32 v70, v46 offset:11440
	ds_write_b32 v70, v47 offset:11444
	ds_write_b32 v70, v48 offset:11448
	ds_write_b32 v70, v49 offset:11452
	s_waitcnt vmcnt(5)
	ds_write_b32 v70, v50 offset:12480
	ds_write_b32 v70, v51 offset:12484
	ds_write_b32 v70, v52 offset:12488
	ds_write_b32 v70, v53 offset:12492
	s_waitcnt vmcnt(4)
	ds_write_b32 v70, v54 offset:13520
	ds_write_b32 v70, v55 offset:13524
	ds_write_b32 v70, v56 offset:13528
	ds_write_b32 v70, v57 offset:13532
	s_waitcnt vmcnt(3)
	ds_write_b32 v70, v58 offset:14560
	ds_write_b32 v70, v59 offset:14564
	ds_write_b32 v70, v60 offset:14568
	ds_write_b32 v70, v61 offset:14572
	s_waitcnt vmcnt(2)
; #define LAS __attribute__((address_space(3)))
; __device__ __forceinline__ unsigned cvtpk(float lo, float hi) { f32x2_t v = {lo, hi}; bf16x2_t b = __builtin_convertvector(v, bf16x2_t); return __builtin_bit_cast(unsigned, b); }
; __device__ __forceinline__ void tr_all(const float* const* in, unsigned char* ws, LAS float* scr, int gw, int ngw, int lane, const TrRanges rg) {
;     ...
;         for (int i = 0; i < 16; ++i) { wp[(4 * i) * 65 + 0] = v[i][0]; wp[(4 * i) * 65 + 1] = v[i][1]; wp[(4 * i) * 65 + 2] = v[i][2]; wp[(4 * i) * 65 + 3] = v[i][3]; }
;         f32x4 g0 = {1.f, 1.f, 1.f, 1.f}, g1 = {1.f, 1.f, 1.f, 1.f};
;         if (cur.gain) { g0 = *(const f32x4*)cur.gain; g1 = *(const f32x4*)(cur.gain + 4); }
;         asm volatile("s_waitcnt lgkmcnt(0)" ::: "memory");
;         const LAS float* rp = scr + (8 * (lane & 7)) * 65 + (lane >> 3);
; #pragma unroll
;         for (int j = 0; j < 8; ++j) { const LAS float* s = rp + 8 * j;
;             u32x4 o; o.x = cvtpk(s[0 * 65] * g0[0], s[1 * 65] * g0[1]); o.y = cvtpk(s[2 * 65] * g0[2], s[3 * 65] * g0[3]);
;             o.z = cvtpk(s[4 * 65] * g1[0], s[5 * 65] * g1[1]); o.w = cvtpk(s[6 * 65] * g1[2], s[7 * 65] * g1[3]);
;             if (cur.nts) __builtin_nontemporal_store(o, (u32x4*)(cur.dst + (size_t)(8 * j) * cur.K)); else *(u32x4*)(cur.dst + (size_t)(8 * j) * cur.K) = o; }
	ds_write_b32 v70, v62 offset:15600
	ds_write_b32 v70, v63 offset:15604
	ds_write_b32 v70, v64 offset:15608
	ds_write_b32 v70, v65 offset:15612
	s_add_u32 s100, s84, 0x8f00000
	s_addc_u32 s101, s85, 0
	s_waitcnt vmcnt(0) lgkmcnt(0)
	ds_read_b32 v2, v71
	ds_read_b32 v3, v71 offset:260
	ds_read_b32 v4, v71 offset:520
	ds_read_b32 v5, v71 offset:780
	ds_read_b32 v6, v71 offset:1040
	ds_read_b32 v7, v71 offset:1300
	ds_read_b32 v8, v71 offset:1560
	ds_read_b32 v9, v71 offset:1820
	ds_read_b32 v10, v71 offset:32
	ds_read_b32 v11, v71 offset:292
	ds_read_b32 v12, v71 offset:552
	ds_read_b32 v13, v71 offset:812
	ds_read_b32 v14, v71 offset:1072
	ds_read_b32 v15, v71 offset:1332
	ds_read_b32 v16, v71 offset:1592
	ds_read_b32 v17, v71 offset:1852
	ds_read_b32 v18, v71 offset:64
	ds_read_b32 v19, v71 offset:324
	ds_read_b32 v20, v71 offset:584
	ds_read_b32 v21, v71 offset:844
	ds_read_b32 v22, v71 offset:1104
	ds_read_b32 v23, v71 offset:1364
	ds_read_b32 v24, v71 offset:1624
	ds_read_b32 v25, v71 offset:1884
	ds_read_b32 v26, v71 offset:96
	ds_read_b32 v27, v71 offset:356
	ds_read_b32 v28, v71 offset:616
	ds_read_b32 v29, v71 offset:876
	ds_read_b32 v30, v71 offset:1136
	ds_read_b32 v31, v71 offset:1396
	ds_read_b32 v32, v71 offset:1656
	ds_read_b32 v33, v71 offset:1916
	ds_read_b32 v34, v71 offset:128
	ds_read_b32 v35, v71 offset:388
	ds_read_b32 v36, v71 offset:648
	ds_read_b32 v37, v71 offset:908
	ds_read_b32 v38, v71 offset:1168
	ds_read_b32 v39, v71 offset:1428
	ds_read_b32 v40, v71 offset:1688
	ds_read_b32 v41, v71 offset:1948
	ds_read_b32 v42, v71 offset:160
	ds_read_b32 v43, v71 offset:420
	ds_read_b32 v44, v71 offset:680
	ds_read_b32 v45, v71 offset:940
	ds_read_b32 v46, v71 offset:1200
	ds_read_b32 v47, v71 offset:1460
	ds_read_b32 v48, v71 offset:1720
	ds_read_b32 v49, v71 offset:1980
	ds_read_b32 v50, v71 offset:192
	ds_read_b32 v51, v71 offset:452
	ds_read_b32 v52, v71 offset:712
	ds_read_b32 v53, v71 offset:972
	ds_read_b32 v54, v71 offset:1232
	ds_read_b32 v55, v71 offset:1492
	ds_read_b32 v56, v71 offset:1752
	ds_read_b32 v57, v71 offset:2012
	ds_read_b32 v58, v71 offset:224
	ds_read_b32 v59, v71 offset:484
	ds_read_b32 v60, v71 offset:744
	ds_read_b32 v61, v71 offset:1004
	ds_read_b32 v62, v71 offset:1264
	ds_read_b32 v63, v71 offset:1524
	ds_read_b32 v64, v71 offset:1784
	ds_read_b32 v65, v71 offset:2044
	s_waitcnt lgkmcnt(15)
	v_mul_f32_e32 v2, v2, v74
	v_mul_f32_e32 v3, v3, v75
	v_mul_f32_e32 v4, v4, v76
	v_mul_f32_e32 v5, v5, v77
	v_mul_f32_e32 v6, v6, v78
	v_mul_f32_e32 v7, v7, v79
	v_mul_f32_e32 v8, v8, v80
	v_mul_f32_e32 v9, v9, v81
	v_cvt_pk_bf16_f32 v192, v2, v3
	v_cvt_pk_bf16_f32 v193, v4, v5
	v_cvt_pk_bf16_f32 v194, v6, v7
	v_cvt_pk_bf16_f32 v195, v8, v9
	global_store_dwordx4 v72, v[192:195], s[100:101] nt
	s_waitcnt lgkmcnt(15)
	v_mul_f32_e32 v10, v10, v74
	v_mul_f32_e32 v11, v11, v75
	v_mul_f32_e32 v12, v12, v76
	v_mul_f32_e32 v13, v13, v77
	v_mul_f32_e32 v14, v14, v78
	v_mul_f32_e32 v15, v15, v79
	v_mul_f32_e32 v16, v16, v80
	v_mul_f32_e32 v17, v17, v81
	v_cvt_pk_bf16_f32 v196, v10, v11
	v_cvt_pk_bf16_f32 v197, v12, v13
	v_cvt_pk_bf16_f32 v198, v14, v15
	v_cvt_pk_bf16_f32 v199, v16, v17
	v_add_u32_e32 v68, 0x8000, v72
	global_store_dwordx4 v68, v[196:199], s[100:101] nt
	s_waitcnt lgkmcnt(15)
	v_mul_f32_e32 v18, v18, v74
	v_mul_f32_e32 v19, v19, v75
	v_mul_f32_e32 v20, v20, v76
	v_mul_f32_e32 v21, v21, v77
	v_mul_f32_e32 v22, v22, v78
	v_mul_f32_e32 v23, v23, v79
	v_mul_f32_e32 v24, v24, v80
	v_mul_f32_e32 v25, v25, v81
	v_cvt_pk_bf16_f32 v200, v18, v19
	v_cvt_pk_bf16_f32 v201, v20, v21
	v_cvt_pk_bf16_f32 v202, v22, v23
	v_cvt_pk_bf16_f32 v203, v24, v25
	v_add_u32_e32 v67, 0x10000, v72
	global_store_dwordx4 v67, v[200:203], s[100:101] nt
	s_waitcnt lgkmcnt(15)
	v_mul_f32_e32 v26, v26, v74
	v_mul_f32_e32 v27, v27, v75
	v_mul_f32_e32 v28, v28, v76
	v_mul_f32_e32 v29, v29, v77
	v_mul_f32_e32 v30, v30, v78
	v_mul_f32_e32 v31, v31, v79
	v_mul_f32_e32 v32, v32, v80
	v_mul_f32_e32 v33, v33, v81
	v_cvt_pk_bf16_f32 v204, v26, v27
	v_cvt_pk_bf16_f32 v205, v28, v29
	v_cvt_pk_bf16_f32 v206, v30, v31
	v_cvt_pk_bf16_f32 v207, v32, v33
	v_add_u32_e32 v68, 0x18000, v72
	global_store_dwordx4 v68, v[204:207], s[100:101] nt
	s_waitcnt lgkmcnt(15)
	v_mul_f32_e32 v34, v34, v74
	v_mul_f32_e32 v35, v35, v75
	v_mul_f32_e32 v36, v36, v76
	v_mul_f32_e32 v37, v37, v77
	v_mul_f32_e32 v38, v38, v78
	v_mul_f32_e32 v39, v39, v79
	v_mul_f32_e32 v40, v40, v80
	v_mul_f32_e32 v41, v41, v81
	v_cvt_pk_bf16_f32 v208, v34, v35
	v_cvt_pk_bf16_f32 v209, v36, v37
	v_cvt_pk_bf16_f32 v210, v38, v39
	v_cvt_pk_bf16_f32 v211, v40, v41
	v_add_u32_e32 v67, 0x20000, v72
	global_store_dwordx4 v67, v[208:211], s[100:101] nt
	s_waitcnt lgkmcnt(15)
	v_mul_f32_e32 v42, v42, v74
	v_mul_f32_e32 v43, v43, v75
	v_mul_f32_e32 v44, v44, v76
	v_mul_f32_e32 v45, v45, v77
	v_mul_f32_e32 v46, v46, v78
	v_mul_f32_e32 v47, v47, v79
	v_mul_f32_e32 v48, v48, v80
	v_mul_f32_e32 v49, v49, v81
	v_cvt_pk_bf16_f32 v212, v42, v43
	v_cvt_pk_bf16_f32 v213, v44, v45
	v_cvt_pk_bf16_f32 v214, v46, v47
	v_cvt_pk_bf16_f32 v215, v48, v49
	v_add_u32_e32 v68, 0x28000, v72
	global_store_dwordx4 v68, v[212:215], s[100:101] nt
	s_waitcnt lgkmcnt(8)
	v_mul_f32_e32 v50, v50, v74
	v_mul_f32_e32 v51, v51, v75
	v_mul_f32_e32 v52, v52, v76
	v_mul_f32_e32 v53, v53, v77
	v_mul_f32_e32 v54, v54, v78
	v_mul_f32_e32 v55, v55, v79
	v_mul_f32_e32 v56, v56, v80
	v_mul_f32_e32 v57, v57, v81
	v_cvt_pk_bf16_f32 v216, v50, v51
	v_cvt_pk_bf16_f32 v217, v52, v53
	v_cvt_pk_bf16_f32 v218, v54, v55
	v_cvt_pk_bf16_f32 v219, v56, v57
	v_add_u32_e32 v67, 0x30000, v72
	global_store_dwordx4 v67, v[216:219], s[100:101] nt
	s_waitcnt lgkmcnt(0)
	v_mul_f32_e32 v58, v58, v74
	v_mul_f32_e32 v59, v59, v75
	v_mul_f32_e32 v60, v60, v76
	v_mul_f32_e32 v61, v61, v77
	v_mul_f32_e32 v62, v62, v78
	v_mul_f32_e32 v63, v63, v79
	v_mul_f32_e32 v64, v64, v80
	v_mul_f32_e32 v65, v65, v81
	v_cvt_pk_bf16_f32 v220, v58, v59
	v_cvt_pk_bf16_f32 v221, v60, v61
	v_cvt_pk_bf16_f32 v222, v62, v63
	v_cvt_pk_bf16_f32 v223, v64, v65
	v_add_u32_e32 v68, 0x38000, v72
	global_store_dwordx4 v68, v[220:223], s[100:101] nt

; #define LAS __attribute__((address_space(3)))
; #define TR_LOAD(p) __builtin_nontemporal_load(p)
; __device__ __forceinline__ TrItem tr_decode(int it, const float* const* in, unsigned char* ws, int lane) {
;     ...
;     const int rh = r >> 3, rl = r & 7, nq = ndb >> DL, kbh = rh / nq, dbh = rh - kbh * nq;
;     const int kb = (kbh << KL) + (rl >> DL), db = (dbh << DL) + (rl & ((1 << DL) - 1)), d0 = db * 64, k0 = kb * 64;
;     ...
;     const int kb = r / ndb, db = r - kb * ndb, d0 = db * 64, k0 = kb * 64;
;     ...
;     const int blk = d0 + 32 * ((lane & 15) >> 3);
;     const float* src = W; int s0 = blk;
;     if (kind == 1) { const int pn = blk >> 8, bj = (blk >> 7) & 1, o = blk & 127; src = bj ? W2 : W; s0 = pn * 128 + o; }
;     else if (kind == 2) s0 = win_src(blk);
;     TrItem t; t.src = src + (size_t)(k0 + (lane >> 4)) * N + s0 + 4 * (lane & 7); t.gain = gain ? gain + k0 + 8 * (lane & 7) : nullptr;
;     t.dst = WT + (size_t)(d0 + (lane >> 3)) * K + k0 + 8 * (lane & 7); t.N = N; t.K = K; t.nts = nts && TR_NTS;
; __device__ __forceinline__ void tr_all(const float* const* in, unsigned char* ws, LAS float* scr, int gw, int ngw, int lane, const TrRanges rg) {
;     ...
;     for (int i = 0; i < 16; ++i) v[i] = TR_LOAD((const f32x4*)(cur.src + (size_t)(4 * i) * cur.N));
;     for (int it = gw; it < TR_CNT; it += ngw) {
;         const int nit = it + ngw; const bool hn = nit < TR_CNT;
;         TrItem nx = cur; f32x4 w[16];
;         if (hn) { nx = tr_decode(rg.item(nit), in, ws, lane);
; #pragma unroll
;             for (int i = 0; i < 16; ++i) w[i] = TR_LOAD((const f32x4*)(nx.src + (size_t)(4 * i) * nx.N)); }
;         LAS float* wp = scr + (lane >> 4) * 65 + 4 * (lane & 15);
; #pragma unroll
;         for (int i = 0; i < 16; ++i) { wp[(4 * i) * 65 + 0] = v[i][0]; wp[(4 * i) * 65 + 1] = v[i][1]; wp[(4 * i) * 65 + 2] = v[i][2]; wp[(4 * i) * 65 + 3] = v[i][3]; }
.Lseam_cv_3:
	s_cmp_lt_u32 s98, 2
	s_cbranch_scc1 .LBB0_1006
	s_cmp_gt_u32 s98, 3
	s_cbranch_scc1 .LBB0_1006
	s_mov_b64 exec, -1
	s_lshl_b32 s99, s87, 1
	s_add_i32 s99, s99, s98
	s_add_i32 s99, s99, 0xbfe
	s_lshr_b32 s100, s99, 3
	s_mul_i32 s101, s100, 0x5d2
	s_lshr_b32 s101, s101, 16
	s_mul_i32 vcc_lo, s101, 44
	s_sub_i32 s100, s100, vcc_lo
	s_and_b32 vcc_lo, s99, 7
	s_lshr_b32 vcc_hi, vcc_lo, 2
	s_lshl_b32 s101, s101, 1
	s_add_i32 s101, s101, vcc_hi
	s_and_b32 vcc_lo, vcc_lo, 3
	s_lshl_b32 s100, s100, 2
	s_add_i32 s100, s100, vcc_lo
	s_lshl_b32 s101, s101, 6
	s_lshl_b32 s100, s100, 6
	v_and_b32_e32 v66, 63, v1
	v_lshrrev_b32_e32 v67, 4, v66
	v_and_b32_e32 v68, 15, v66
	v_and_b32_e32 v73, 7, v66
	v_lshrrev_b32_e32 v72, 3, v66
	s_mul_i32 s99, s98, 0x4100
	v_mul_u32_u24_e32 v70, 0x104, v67
	v_lshl_add_u32 v70, v68, 4, v70
	v_add_u32_e32 v70, s99, v70
	v_mul_u32_u24_e32 v71, 0x820, v73
	v_lshl_add_u32 v71, v72, 2, v71
	v_add_u32_e32 v71, s99, v71
	s_mul_i32 s99, s101, 0x1600
	s_lshr_b32 vcc_lo, s100, 8
	s_lshl_b32 vcc_lo, vcc_lo, 7
	s_add_i32 s99, s99, vcc_lo
	s_and_b32 vcc_lo, s100, 0x7f
	s_add_i32 s99, s99, vcc_lo
	s_lshl_b32 s99, s99, 2
	v_mul_u32_u24_e32 v69, 0x5800, v67
	v_lshl_add_u32 v69, v68, 4, v69
	v_add_u32_e32 v69, s99, v69
	s_lshl_b32 s99, s100, 12
	s_lshl_b32 vcc_lo, s101, 1
	s_add_i32 s99, s99, vcc_lo
	v_lshlrev_b32_e32 v72, 12, v72
	v_lshl_add_u32 v72, v73, 4, v72
	v_add_u32_e32 v72, s99, v72
	s_lshl_b32 s99, s101, 2
	v_lshlrev_b32_e32 v73, 5, v73
	v_add_u32_e32 v73, s99, v73
	s_nop 0
	s_bitcmp1_b32 s100, 7
	v_readlane_b32 s100, v254, 6
	v_readlane_b32 s101, v254, 7
	v_readlane_b32 s98, v254, 8
	v_readlane_b32 s99, v254, 9
	s_nop 3
	s_cselect_b32 s100, s98, s100
	s_cselect_b32 s101, s99, s101
	v_readlane_b32 s98, v254, 4
	v_readlane_b32 s99, v254, 5
	global_load_dwordx4 v[2:5], v69, s[100:101] nt
	v_add_u32_e32 v68, 0x16000, v69
	global_load_dwordx4 v[6:9], v68, s[100:101] nt
	v_add_u32_e32 v67, 0x2c000, v69
	global_load_dwordx4 v[10:13], v67, s[100:101] nt
	v_add_u32_e32 v68, 0x42000, v69
	global_load_dwordx4 v[14:17], v68, s[100:101] nt
	v_add_u32_e32 v67, 0x58000, v69
	global_load_dwordx4 v[18:21], v67, s[100:101] nt
	v_add_u32_e32 v68, 0x6e000, v69
	global_load_dwordx4 v[22:25], v68, s[100:101] nt
	v_add_u32_e32 v67, 0x84000, v69
	global_load_dwordx4 v[26:29], v67, s[100:101] nt
	v_add_u32_e32 v68, 0x9a000, v69
	global_load_dwordx4 v[30:33], v68, s[100:101] nt
	v_add_u32_e32 v67, 0xb0000, v69
	global_load_dwordx4 v[34:37], v67, s[100:101] nt
	v_add_u32_e32 v68, 0xc6000, v69
	global_load_dwordx4 v[38:41], v68, s[100:101] nt
	v_add_u32_e32 v67, 0xdc000, v69
	global_load_dwordx4 v[42:45], v67, s[100:101] nt
	v_add_u32_e32 v68, 0xf2000, v69
	global_load_dwordx4 v[46:49], v68, s[100:101] nt
	v_add_u32_e32 v67, 0x108000, v69
	global_load_dwordx4 v[50:53], v67, s[100:101] nt
	v_add_u32_e32 v68, 0x11e000, v69
	global_load_dwordx4 v[54:57], v68, s[100:101] nt
	v_add_u32_e32 v67, 0x134000, v69
	global_load_dwordx4 v[58:61], v67, s[100:101] nt
	v_add_u32_e32 v68, 0x14a000, v69
	global_load_dwordx4 v[62:65], v68, s[100:101] nt
	global_load_dwordx4 v[74:77], v73, s[98:99]
	global_load_dwordx4 v[78:81], v73, s[98:99] offset:16
	s_waitcnt vmcnt(17)
	ds_write_b32 v70, v2
	ds_write_b32 v70, v3 offset:4
	ds_write_b32 v70, v4 offset:8
	ds_write_b32 v70, v5 offset:12
	s_waitcnt vmcnt(16)
	ds_write_b32 v70, v6 offset:1040
	ds_write_b32 v70, v7 offset:1044
	ds_write_b32 v70, v8 offset:1048
	ds_write_b32 v70, v9 offset:1052
	s_waitcnt vmcnt(15)
	ds_write_b32 v70, v10 offset:2080
	ds_write_b32 v70, v11 offset:2084
	ds_write_b32 v70, v12 offset:2088
	ds_write_b32 v70, v13 offset:2092
	s_waitcnt vmcnt(14)
	ds_write_b32 v70, v14 offset:3120
	ds_write_b32 v70, v15 offset:3124
	ds_write_b32 v70, v16 offset:3128
	ds_write_b32 v70, v17 offset:3132
	s_waitcnt vmcnt(13)
	ds_write_b32 v70, v18 offset:4160
	ds_write_b32 v70, v19 offset:4164
	ds_write_b32 v70, v20 offset:4168
	ds_write_b32 v70, v21 offset:4172
	s_waitcnt vmcnt(12)
	ds_write_b32 v70, v22 offset:5200
	ds_write_b32 v70, v23 offset:5204
	ds_write_b32 v70, v24 offset:5208
	ds_write_b32 v70, v25 offset:5212
	s_waitcnt vmcnt(11)
	ds_write_b32 v70, v26 offset:6240
	ds_write_b32 v70, v27 offset:6244
	ds_write_b32 v70, v28 offset:6248
	ds_write_b32 v70, v29 offset:6252
	s_waitcnt vmcnt(10)
	ds_write_b32 v70, v30 offset:7280
	ds_write_b32 v70, v31 offset:7284
	ds_write_b32 v70, v32 offset:7288
	ds_write_b32 v70, v33 offset:7292
	s_waitcnt vmcnt(9)
	ds_write_b32 v70, v34 offset:8320
	ds_write_b32 v70, v35 offset:8324
	ds_write_b32 v70, v36 offset:8328
	ds_write_b32 v70, v37 offset:8332
	s_waitcnt vmcnt(8)
	ds_write_b32 v70, v38 offset:9360
	ds_write_b32 v70, v39 offset:9364
	ds_write_b32 v70, v40 offset:9368
	ds_write_b32 v70, v41 offset:9372
	s_waitcnt vmcnt(7)
	ds_write_b32 v70, v42 offset:10400
	ds_write_b32 v70, v43 offset:10404
	ds_write_b32 v70, v44 offset:10408
	ds_write_b32 v70, v45 offset:10412
	s_waitcnt vmcnt(6)
	ds_write_b32 v70, v46 offset:11440
	ds_write_b32 v70, v47 offset:11444
	ds_write_b32 v70, v48 offset:11448
	ds_write_b32 v70, v49 offset:11452
	s_waitcnt vmcnt(5)
	ds_write_b32 v70, v50 offset:12480
	ds_write_b32 v70, v51 offset:12484
	ds_write_b32 v70, v52 offset:12488
	ds_write_b32 v70, v53 offset:12492
	s_waitcnt vmcnt(4)
	ds_write_b32 v70, v54 offset:13520
	ds_write_b32 v70, v55 offset:13524
	ds_write_b32 v70, v56 offset:13528
	ds_write_b32 v70, v57 offset:13532
	s_waitcnt vmcnt(3)
	ds_write_b32 v70, v58 offset:14560
	ds_write_b32 v70, v59 offset:14564
	ds_write_b32 v70, v60 offset:14568
	ds_write_b32 v70, v61 offset:14572
	s_waitcnt vmcnt(2)
; #define LAS __attribute__((address_space(3)))
; __device__ __forceinline__ unsigned cvtpk(float lo, float hi) { f32x2_t v = {lo, hi}; bf16x2_t b = __builtin_convertvector(v, bf16x2_t); return __builtin_bit_cast(unsigned, b); }
; __device__ __forceinline__ void tr_all(const float* const* in, unsigned char* ws, LAS float* scr, int gw, int ngw, int lane, const TrRanges rg) {
;     ...
;         for (int i = 0; i < 16; ++i) { wp[(4 * i) * 65 + 0] = v[i][0]; wp[(4 * i) * 65 + 1] = v[i][1]; wp[(4 * i) * 65 + 2] = v[i][2]; wp[(4 * i) * 65 + 3] = v[i][3]; }
;         f32x4 g0 = {1.f, 1.f, 1.f, 1.f}, g1 = {1.f, 1.f, 1.f, 1.f};
;         if (cur.gain) { g0 = *(const f32x4*)cur.gain; g1 = *(const f32x4*)(cur.gain + 4); }
;         asm volatile("s_waitcnt lgkmcnt(0)" ::: "memory");
;         const LAS float* rp = scr + (8 * (lane & 7)) * 65 + (lane >> 3);
; #pragma unroll
;         for (int j = 0; j < 8; ++j) { const LAS float* s = rp + 8 * j;
;             u32x4 o; o.x = cvtpk(s[0 * 65] * g0[0], s[1 * 65] * g0[1]); o.y = cvtpk(s[2 * 65] * g0[2], s[3 * 65] * g0[3]);
;             o.z = cvtpk(s[4 * 65] * g1[0], s[5 * 65] * g1[1]); o.w = cvtpk(s[6 * 65] * g1[2], s[7 * 65] * g1[3]);
;             if (cur.nts) __builtin_nontemporal_store(o, (u32x4*)(cur.dst + (size_t)(8 * j) * cur.K)); else *(u32x4*)(cur.dst + (size_t)(8 * j) * cur.K) = o; }
	ds_write_b32 v70, v62 offset:15600
	ds_write_b32 v70, v63 offset:15604
	ds_write_b32 v70, v64 offset:15608
	ds_write_b32 v70, v65 offset:15612
	s_add_u32 s100, s84, 0x8f00000
	s_addc_u32 s101, s85, 0
	s_waitcnt vmcnt(0) lgkmcnt(0)
	ds_read_b32 v2, v71
	ds_read_b32 v3, v71 offset:260
	ds_read_b32 v4, v71 offset:520
	ds_read_b32 v5, v71 offset:780
	ds_read_b32 v6, v71 offset:1040
	ds_read_b32 v7, v71 offset:1300
	ds_read_b32 v8, v71 offset:1560
	ds_read_b32 v9, v71 offset:1820
	ds_read_b32 v10, v71 offset:32
	ds_read_b32 v11, v71 offset:292
	ds_read_b32 v12, v71 offset:552
	ds_read_b32 v13, v71 offset:812
	ds_read_b32 v14, v71 offset:1072
	ds_read_b32 v15, v71 offset:1332
	ds_read_b32 v16, v71 offset:1592
	ds_read_b32 v17, v71 offset:1852
	ds_read_b32 v18, v71 offset:64
	ds_read_b32 v19, v71 offset:324
	ds_read_b32 v20, v71 offset:584
	ds_read_b32 v21, v71 offset:844
	ds_read_b32 v22, v71 offset:1104
	ds_read_b32 v23, v71 offset:1364
	ds_read_b32 v24, v71 offset:1624
	ds_read_b32 v25, v71 offset:1884
	ds_read_b32 v26, v71 offset:96
	ds_read_b32 v27, v71 offset:356
	ds_read_b32 v28, v71 offset:616
	ds_read_b32 v29, v71 offset:876
	ds_read_b32 v30, v71 offset:1136
	ds_read_b32 v31, v71 offset:1396
	ds_read_b32 v32, v71 offset:1656
	ds_read_b32 v33, v71 offset:1916
	ds_read_b32 v34, v71 offset:128
	ds_read_b32 v35, v71 offset:388
	ds_read_b32 v36, v71 offset:648
	ds_read_b32 v37, v71 offset:908
	ds_read_b32 v38, v71 offset:1168
	ds_read_b32 v39, v71 offset:1428
	ds_read_b32 v40, v71 offset:1688
	ds_read_b32 v41, v71 offset:1948
	ds_read_b32 v42, v71 offset:160
	ds_read_b32 v43, v71 offset:420
	ds_read_b32 v44, v71 offset:680
	ds_read_b32 v45, v71 offset:940
	ds_read_b32 v46, v71 offset:1200
	ds_read_b32 v47, v71 offset:1460
	ds_read_b32 v48, v71 offset:1720
	ds_read_b32 v49, v71 offset:1980
	ds_read_b32 v50, v71 offset:192
	ds_read_b32 v51, v71 offset:452
	ds_read_b32 v52, v71 offset:712
	ds_read_b32 v53, v71 offset:972
	ds_read_b32 v54, v71 offset:1232
	ds_read_b32 v55, v71 offset:1492
	ds_read_b32 v56, v71 offset:1752
	ds_read_b32 v57, v71 offset:2012
	ds_read_b32 v58, v71 offset:224
	ds_read_b32 v59, v71 offset:484
	ds_read_b32 v60, v71 offset:744
	ds_read_b32 v61, v71 offset:1004
	ds_read_b32 v62, v71 offset:1264
	ds_read_b32 v63, v71 offset:1524
	ds_read_b32 v64, v71 offset:1784
	ds_read_b32 v65, v71 offset:2044
	s_waitcnt lgkmcnt(15)
	v_mul_f32_e32 v2, v2, v74
	v_mul_f32_e32 v3, v3, v75
	v_mul_f32_e32 v4, v4, v76
	v_mul_f32_e32 v5, v5, v77
	v_mul_f32_e32 v6, v6, v78
	v_mul_f32_e32 v7, v7, v79
	v_mul_f32_e32 v8, v8, v80
	v_mul_f32_e32 v9, v9, v81
	v_cvt_pk_bf16_f32 v192, v2, v3
	v_cvt_pk_bf16_f32 v193, v4, v5
	v_cvt_pk_bf16_f32 v194, v6, v7
	v_cvt_pk_bf16_f32 v195, v8, v9
	global_store_dwordx4 v72, v[192:195], s[100:101] nt
	s_waitcnt lgkmcnt(15)
	v_mul_f32_e32 v10, v10, v74
	v_mul_f32_e32 v11, v11, v75
	v_mul_f32_e32 v12, v12, v76
	v_mul_f32_e32 v13, v13, v77
	v_mul_f32_e32 v14, v14, v78
	v_mul_f32_e32 v15, v15, v79
	v_mul_f32_e32 v16, v16, v80
	v_mul_f32_e32 v17, v17, v81
	v_cvt_pk_bf16_f32 v196, v10, v11
	v_cvt_pk_bf16_f32 v197, v12, v13
	v_cvt_pk_bf16_f32 v198, v14, v15
	v_cvt_pk_bf16_f32 v199, v16, v17
	v_add_u32_e32 v68, 0x8000, v72
	global_store_dwordx4 v68, v[196:199], s[100:101] nt
	s_waitcnt lgkmcnt(15)
	v_mul_f32_e32 v18, v18, v74
	v_mul_f32_e32 v19, v19, v75
	v_mul_f32_e32 v20, v20, v76
	v_mul_f32_e32 v21, v21, v77
	v_mul_f32_e32 v22, v22, v78
	v_mul_f32_e32 v23, v23, v79
	v_mul_f32_e32 v24, v24, v80
	v_mul_f32_e32 v25, v25, v81
	v_cvt_pk_bf16_f32 v200, v18, v19
	v_cvt_pk_bf16_f32 v201, v20, v21
	v_cvt_pk_bf16_f32 v202, v22, v23
	v_cvt_pk_bf16_f32 v203, v24, v25
	v_add_u32_e32 v67, 0x10000, v72
	global_store_dwordx4 v67, v[200:203], s[100:101] nt
	s_waitcnt lgkmcnt(15)
	v_mul_f32_e32 v26, v26, v74
	v_mul_f32_e32 v27, v27, v75
	v_mul_f32_e32 v28, v28, v76
	v_mul_f32_e32 v29, v29, v77
	v_mul_f32_e32 v30, v30, v78
	v_mul_f32_e32 v31, v31, v79
	v_mul_f32_e32 v32, v32, v80
	v_mul_f32_e32 v33, v33, v81
	v_cvt_pk_bf16_f32 v204, v26, v27
	v_cvt_pk_bf16_f32 v205, v28, v29
	v_cvt_pk_bf16_f32 v206, v30, v31
	v_cvt_pk_bf16_f32 v207, v32, v33
	v_add_u32_e32 v68, 0x18000, v72
	global_store_dwordx4 v68, v[204:207], s[100:101] nt
	s_waitcnt lgkmcnt(15)
	v_mul_f32_e32 v34, v34, v74
	v_mul_f32_e32 v35, v35, v75
	v_mul_f32_e32 v36, v36, v76
	v_mul_f32_e32 v37, v37, v77
	v_mul_f32_e32 v38, v38, v78
	v_mul_f32_e32 v39, v39, v79
	v_mul_f32_e32 v40, v40, v80
	v_mul_f32_e32 v41, v41, v81
	v_cvt_pk_bf16_f32 v208, v34, v35
	v_cvt_pk_bf16_f32 v209, v36, v37
	v_cvt_pk_bf16_f32 v210, v38, v39
	v_cvt_pk_bf16_f32 v211, v40, v41
	v_add_u32_e32 v67, 0x20000, v72
	global_store_dwordx4 v67, v[208:211], s[100:101] nt
	s_waitcnt lgkmcnt(15)
	v_mul_f32_e32 v42, v42, v74
	v_mul_f32_e32 v43, v43, v75
	v_mul_f32_e32 v44, v44, v76
	v_mul_f32_e32 v45, v45, v77
	v_mul_f32_e32 v46, v46, v78
	v_mul_f32_e32 v47, v47, v79
	v_mul_f32_e32 v48, v48, v80
	v_mul_f32_e32 v49, v49, v81
	v_cvt_pk_bf16_f32 v212, v42, v43
	v_cvt_pk_bf16_f32 v213, v44, v45
	v_cvt_pk_bf16_f32 v214, v46, v47
	v_cvt_pk_bf16_f32 v215, v48, v49
	v_add_u32_e32 v68, 0x28000, v72
	global_store_dwordx4 v68, v[212:215], s[100:101] nt
	s_waitcnt lgkmcnt(8)
	v_mul_f32_e32 v50, v50, v74
	v_mul_f32_e32 v51, v51, v75
	v_mul_f32_e32 v52, v52, v76
	v_mul_f32_e32 v53, v53, v77
	v_mul_f32_e32 v54, v54, v78
	v_mul_f32_e32 v55, v55, v79
	v_mul_f32_e32 v56, v56, v80
	v_mul_f32_e32 v57, v57, v81
	v_cvt_pk_bf16_f32 v216, v50, v51
	v_cvt_pk_bf16_f32 v217, v52, v53
	v_cvt_pk_bf16_f32 v218, v54, v55
	v_cvt_pk_bf16_f32 v219, v56, v57
	v_add_u32_e32 v67, 0x30000, v72
	global_store_dwordx4 v67, v[216:219], s[100:101] nt
	s_waitcnt lgkmcnt(0)
	v_mul_f32_e32 v58, v58, v74
	v_mul_f32_e32 v59, v59, v75
	v_mul_f32_e32 v60, v60, v76
	v_mul_f32_e32 v61, v61, v77
	v_mul_f32_e32 v62, v62, v78
	v_mul_f32_e32 v63, v63, v79
	v_mul_f32_e32 v64, v64, v80
	v_mul_f32_e32 v65, v65, v81
	v_cvt_pk_bf16_f32 v220, v58, v59
	v_cvt_pk_bf16_f32 v221, v60, v61
	v_cvt_pk_bf16_f32 v222, v62, v63
	v_cvt_pk_bf16_f32 v223, v64, v65
	v_add_u32_e32 v68, 0x38000, v72
	global_store_dwordx4 v68, v[220:223], s[100:101] nt

; #define LAS __attribute__((address_space(3)))
; #define TR_LOAD(p) __builtin_nontemporal_load(p)
; __device__ __forceinline__ TrItem tr_decode(int it, const float* const* in, unsigned char* ws, int lane) {
;     ...
;     const int rh = r >> 3, rl = r & 7, nq = ndb >> DL, kbh = rh / nq, dbh = rh - kbh * nq;
;     const int kb = (kbh << KL) + (rl >> DL), db = (dbh << DL) + (rl & ((1 << DL) - 1)), d0 = db * 64, k0 = kb * 64;
;     ...
;     const int kb = r / ndb, db = r - kb * ndb, d0 = db * 64, k0 = kb * 64;
;     ...
;     const int blk = d0 + 32 * ((lane & 15) >> 3);
;     const float* src = W; int s0 = blk;
;     if (kind == 1) { const int pn = blk >> 8, bj = (blk >> 7) & 1, o = blk & 127; src = bj ? W2 : W; s0 = pn * 128 + o; }
;     else if (kind == 2) s0 = win_src(blk);
;     TrItem t; t.src = src + (size_t)(k0 + (lane >> 4)) * N + s0 + 4 * (lane & 7); t.gain = gain ? gain + k0 + 8 * (lane & 7) : nullptr;
;     t.dst = WT + (size_t)(d0 + (lane >> 3)) * K + k0 + 8 * (lane & 7); t.N = N; t.K = K; t.nts = nts && TR_NTS;
; __device__ __forceinline__ void tr_all(const float* const* in, unsigned char* ws, LAS float* scr, int gw, int ngw, int lane, const TrRanges rg) {
;     ...
;     for (int i = 0; i < 16; ++i) v[i] = TR_LOAD((const f32x4*)(cur.src + (size_t)(4 * i) * cur.N));
;     for (int it = gw; it < TR_CNT; it += ngw) {
;         const int nit = it + ngw; const bool hn = nit < TR_CNT;
;         TrItem nx = cur; f32x4 w[16];
;         if (hn) { nx = tr_decode(rg.item(nit), in, ws, lane);
; #pragma unroll
;             for (int i = 0; i < 16; ++i) w[i] = TR_LOAD((const f32x4*)(nx.src + (size_t)(4 * i) * nx.N)); }
;         LAS float* wp = scr + (lane >> 4) * 65 + 4 * (lane & 15);
; #pragma unroll
;         for (int i = 0; i < 16; ++i) { wp[(4 * i) * 65 + 0] = v[i][0]; wp[(4 * i) * 65 + 1] = v[i][1]; wp[(4 * i) * 65 + 2] = v[i][2]; wp[(4 * i) * 65 + 3] = v[i][3]; }
.Lseam_cv_6:
	s_cmp_lt_u32 s98, 2
	s_cbranch_scc1 .LBB0_1296
	s_cmp_gt_u32 s98, 3
	s_cbranch_scc1 .LBB0_1296
	s_mov_b64 exec, -1
	s_lshl_b32 s99, s87, 1
	s_add_i32 s99, s99, s98
	s_add_i32 s99, s99, 0xdfe
	s_lshr_b32 s100, s99, 3
	s_mul_i32 s101, s100, 0x5d2
	s_lshr_b32 s101, s101, 16
	s_mul_i32 vcc_lo, s101, 44
	s_sub_i32 s100, s100, vcc_lo
	s_and_b32 vcc_lo, s99, 7
	s_lshr_b32 vcc_hi, vcc_lo, 2
	s_lshl_b32 s101, s101, 1
	s_add_i32 s101, s101, vcc_hi
	s_and_b32 vcc_lo, vcc_lo, 3
	s_lshl_b32 s100, s100, 2
	s_add_i32 s100, s100, vcc_lo
	s_lshl_b32 s101, s101, 6
	s_lshl_b32 s100, s100, 6
	v_and_b32_e32 v66, 63, v1
	v_lshrrev_b32_e32 v67, 4, v66
	v_and_b32_e32 v68, 15, v66
	v_and_b32_e32 v73, 7, v66
	v_lshrrev_b32_e32 v72, 3, v66
	s_mul_i32 s99, s98, 0x4100
	v_mul_u32_u24_e32 v70, 0x104, v67
	v_lshl_add_u32 v70, v68, 4, v70
	v_add_u32_e32 v70, s99, v70
	v_mul_u32_u24_e32 v71, 0x820, v73
	v_lshl_add_u32 v71, v72, 2, v71
	v_add_u32_e32 v71, s99, v71
	s_mul_i32 s99, s101, 0x1600
	s_lshr_b32 vcc_lo, s100, 8
	s_lshl_b32 vcc_lo, vcc_lo, 7
	s_add_i32 s99, s99, vcc_lo
	s_and_b32 vcc_lo, s100, 0x7f
	s_add_i32 s99, s99, vcc_lo
	s_lshl_b32 s99, s99, 2
	v_mul_u32_u24_e32 v69, 0x5800, v67
	v_lshl_add_u32 v69, v68, 4, v69
	v_add_u32_e32 v69, s99, v69
	s_lshl_b32 s99, s100, 12
	s_lshl_b32 vcc_lo, s101, 1
	s_add_i32 s99, s99, vcc_lo
	v_lshlrev_b32_e32 v72, 12, v72
	v_lshl_add_u32 v72, v73, 4, v72
	v_add_u32_e32 v72, s99, v72
	s_lshl_b32 s99, s101, 2
	v_lshlrev_b32_e32 v73, 5, v73
	v_add_u32_e32 v73, s99, v73
	s_nop 0
	s_bitcmp1_b32 s100, 7
	v_readlane_b32 s100, v254, 6
	v_readlane_b32 s101, v254, 7
	v_readlane_b32 s98, v254, 8
	v_readlane_b32 s99, v254, 9
	s_nop 3
	s_cselect_b32 s100, s98, s100
	s_cselect_b32 s101, s99, s101
	v_readlane_b32 s98, v254, 4
	v_readlane_b32 s99, v254, 5
	global_load_dwordx4 v[2:5], v69, s[100:101] nt
	v_add_u32_e32 v68, 0x16000, v69
	global_load_dwordx4 v[6:9], v68, s[100:101] nt
	v_add_u32_e32 v67, 0x2c000, v69
	global_load_dwordx4 v[10:13], v67, s[100:101] nt
	v_add_u32_e32 v68, 0x42000, v69
	global_load_dwordx4 v[14:17], v68, s[100:101] nt
	v_add_u32_e32 v67, 0x58000, v69
	global_load_dwordx4 v[18:21], v67, s[100:101] nt
	v_add_u32_e32 v68, 0x6e000, v69
	global_load_dwordx4 v[22:25], v68, s[100:101] nt
	v_add_u32_e32 v67, 0x84000, v69
	global_load_dwordx4 v[26:29], v67, s[100:101] nt
	v_add_u32_e32 v68, 0x9a000, v69
	global_load_dwordx4 v[30:33], v68, s[100:101] nt
	v_add_u32_e32 v67, 0xb0000, v69
	global_load_dwordx4 v[34:37], v67, s[100:101] nt
	v_add_u32_e32 v68, 0xc6000, v69
	global_load_dwordx4 v[38:41], v68, s[100:101] nt
	v_add_u32_e32 v67, 0xdc000, v69
	global_load_dwordx4 v[42:45], v67, s[100:101] nt
	v_add_u32_e32 v68, 0xf2000, v69
	global_load_dwordx4 v[46:49], v68, s[100:101] nt
	v_add_u32_e32 v67, 0x108000, v69
	global_load_dwordx4 v[50:53], v67, s[100:101] nt
	v_add_u32_e32 v68, 0x11e000, v69
	global_load_dwordx4 v[54:57], v68, s[100:101] nt
	v_add_u32_e32 v67, 0x134000, v69
	global_load_dwordx4 v[58:61], v67, s[100:101] nt
	v_add_u32_e32 v68, 0x14a000, v69
	global_load_dwordx4 v[62:65], v68, s[100:101] nt
	global_load_dwordx4 v[74:77], v73, s[98:99]
	global_load_dwordx4 v[78:81], v73, s[98:99] offset:16
	s_waitcnt vmcnt(17)
	ds_write_b32 v70, v2
	ds_write_b32 v70, v3 offset:4
	ds_write_b32 v70, v4 offset:8
	ds_write_b32 v70, v5 offset:12
	s_waitcnt vmcnt(16)
	ds_write_b32 v70, v6 offset:1040
	ds_write_b32 v70, v7 offset:1044
	ds_write_b32 v70, v8 offset:1048
	ds_write_b32 v70, v9 offset:1052
	s_waitcnt vmcnt(15)
	ds_write_b32 v70, v10 offset:2080
	ds_write_b32 v70, v11 offset:2084
	ds_write_b32 v70, v12 offset:2088
	ds_write_b32 v70, v13 offset:2092
	s_waitcnt vmcnt(14)
	ds_write_b32 v70, v14 offset:3120
	ds_write_b32 v70, v15 offset:3124
	ds_write_b32 v70, v16 offset:3128
	ds_write_b32 v70, v17 offset:3132
	s_waitcnt vmcnt(13)
	ds_write_b32 v70, v18 offset:4160
	ds_write_b32 v70, v19 offset:4164
	ds_write_b32 v70, v20 offset:4168
	ds_write_b32 v70, v21 offset:4172
	s_waitcnt vmcnt(12)
	ds_write_b32 v70, v22 offset:5200
	ds_write_b32 v70, v23 offset:5204
	ds_write_b32 v70, v24 offset:5208
	ds_write_b32 v70, v25 offset:5212
	s_waitcnt vmcnt(11)
	ds_write_b32 v70, v26 offset:6240
	ds_write_b32 v70, v27 offset:6244
	ds_write_b32 v70, v28 offset:6248
	ds_write_b32 v70, v29 offset:6252
	s_waitcnt vmcnt(10)
	ds_write_b32 v70, v30 offset:7280
	ds_write_b32 v70, v31 offset:7284
	ds_write_b32 v70, v32 offset:7288
	ds_write_b32 v70, v33 offset:7292
	s_waitcnt vmcnt(9)
	ds_write_b32 v70, v34 offset:8320
	ds_write_b32 v70, v35 offset:8324
	ds_write_b32 v70, v36 offset:8328
	ds_write_b32 v70, v37 offset:8332
	s_waitcnt vmcnt(8)
	ds_write_b32 v70, v38 offset:9360
	ds_write_b32 v70, v39 offset:9364
	ds_write_b32 v70, v40 offset:9368
	ds_write_b32 v70, v41 offset:9372
	s_waitcnt vmcnt(7)
	ds_write_b32 v70, v42 offset:10400
	ds_write_b32 v70, v43 offset:10404
	ds_write_b32 v70, v44 offset:10408
	ds_write_b32 v70, v45 offset:10412
	s_waitcnt vmcnt(6)
	ds_write_b32 v70, v46 offset:11440
	ds_write_b32 v70, v47 offset:11444
	ds_write_b32 v70, v48 offset:11448
	ds_write_b32 v70, v49 offset:11452
	s_waitcnt vmcnt(5)
	ds_write_b32 v70, v50 offset:12480
	ds_write_b32 v70, v51 offset:12484
	ds_write_b32 v70, v52 offset:12488
	ds_write_b32 v70, v53 offset:12492
	s_waitcnt vmcnt(4)
	ds_write_b32 v70, v54 offset:13520
	ds_write_b32 v70, v55 offset:13524
	ds_write_b32 v70, v56 offset:13528
	ds_write_b32 v70, v57 offset:13532
	s_waitcnt vmcnt(3)
	ds_write_b32 v70, v58 offset:14560
	ds_write_b32 v70, v59 offset:14564
	ds_write_b32 v70, v60 offset:14568
	ds_write_b32 v70, v61 offset:14572
	s_waitcnt vmcnt(2)
; #define LAS __attribute__((address_space(3)))
; __device__ __forceinline__ unsigned cvtpk(float lo, float hi) { f32x2_t v = {lo, hi}; bf16x2_t b = __builtin_convertvector(v, bf16x2_t); return __builtin_bit_cast(unsigned, b); }
; __device__ __forceinline__ void tr_all(const float* const* in, unsigned char* ws, LAS float* scr, int gw, int ngw, int lane, const TrRanges rg) {
;     ...
;         for (int i = 0; i < 16; ++i) { wp[(4 * i) * 65 + 0] = v[i][0]; wp[(4 * i) * 65 + 1] = v[i][1]; wp[(4 * i) * 65 + 2] = v[i][2]; wp[(4 * i) * 65 + 3] = v[i][3]; }
;         f32x4 g0 = {1.f, 1.f, 1.f, 1.f}, g1 = {1.f, 1.f, 1.f, 1.f};
;         if (cur.gain) { g0 = *(const f32x4*)cur.gain; g1 = *(const f32x4*)(cur.gain + 4); }
;         asm volatile("s_waitcnt lgkmcnt(0)" ::: "memory");
;         const LAS float* rp = scr + (8 * (lane & 7)) * 65 + (lane >> 3);
; #pragma unroll
;         for (int j = 0; j < 8; ++j) { const LAS float* s = rp + 8 * j;
;             u32x4 o; o.x = cvtpk(s[0 * 65] * g0[0], s[1 * 65] * g0[1]); o.y = cvtpk(s[2 * 65] * g0[2], s[3 * 65] * g0[3]);
;             o.z = cvtpk(s[4 * 65] * g1[0], s[5 * 65] * g1[1]); o.w = cvtpk(s[6 * 65] * g1[2], s[7 * 65] * g1[3]);
;             if (cur.nts) __builtin_nontemporal_store(o, (u32x4*)(cur.dst + (size_t)(8 * j) * cur.K)); else *(u32x4*)(cur.dst + (size_t)(8 * j) * cur.K) = o; }
	ds_write_b32 v70, v62 offset:15600
	ds_write_b32 v70, v63 offset:15604
	ds_write_b32 v70, v64 offset:15608
	ds_write_b32 v70, v65 offset:15612
	s_add_u32 s100, s84, 0x8f00000
	s_addc_u32 s101, s85, 0
	s_waitcnt vmcnt(0) lgkmcnt(0)
	ds_read_b32 v2, v71
	ds_read_b32 v3, v71 offset:260
	ds_read_b32 v4, v71 offset:520
	ds_read_b32 v5, v71 offset:780
	ds_read_b32 v6, v71 offset:1040
	ds_read_b32 v7, v71 offset:1300
	ds_read_b32 v8, v71 offset:1560
	ds_read_b32 v9, v71 offset:1820
	ds_read_b32 v10, v71 offset:32
	ds_read_b32 v11, v71 offset:292
	ds_read_b32 v12, v71 offset:552
	ds_read_b32 v13, v71 offset:812
	ds_read_b32 v14, v71 offset:1072
	ds_read_b32 v15, v71 offset:1332
	ds_read_b32 v16, v71 offset:1592
	ds_read_b32 v17, v71 offset:1852
	ds_read_b32 v18, v71 offset:64
	ds_read_b32 v19, v71 offset:324
	ds_read_b32 v20, v71 offset:584
	ds_read_b32 v21, v71 offset:844
	ds_read_b32 v22, v71 offset:1104
	ds_read_b32 v23, v71 offset:1364
	ds_read_b32 v24, v71 offset:1624
	ds_read_b32 v25, v71 offset:1884
	ds_read_b32 v26, v71 offset:96
	ds_read_b32 v27, v71 offset:356
	ds_read_b32 v28, v71 offset:616
	ds_read_b32 v29, v71 offset:876
	ds_read_b32 v30, v71 offset:1136
	ds_read_b32 v31, v71 offset:1396
	ds_read_b32 v32, v71 offset:1656
	ds_read_b32 v33, v71 offset:1916
	ds_read_b32 v34, v71 offset:128
	ds_read_b32 v35, v71 offset:388
	ds_read_b32 v36, v71 offset:648
	ds_read_b32 v37, v71 offset:908
	ds_read_b32 v38, v71 offset:1168
	ds_read_b32 v39, v71 offset:1428
	ds_read_b32 v40, v71 offset:1688
	ds_read_b32 v41, v71 offset:1948
	ds_read_b32 v42, v71 offset:160
	ds_read_b32 v43, v71 offset:420
	ds_read_b32 v44, v71 offset:680
	ds_read_b32 v45, v71 offset:940
	ds_read_b32 v46, v71 offset:1200
	ds_read_b32 v47, v71 offset:1460
	ds_read_b32 v48, v71 offset:1720
	ds_read_b32 v49, v71 offset:1980
	ds_read_b32 v50, v71 offset:192
	ds_read_b32 v51, v71 offset:452
	ds_read_b32 v52, v71 offset:712
	ds_read_b32 v53, v71 offset:972
	ds_read_b32 v54, v71 offset:1232
	ds_read_b32 v55, v71 offset:1492
	ds_read_b32 v56, v71 offset:1752
	ds_read_b32 v57, v71 offset:2012
	ds_read_b32 v58, v71 offset:224
	ds_read_b32 v59, v71 offset:484
	ds_read_b32 v60, v71 offset:744
	ds_read_b32 v61, v71 offset:1004
	ds_read_b32 v62, v71 offset:1264
	ds_read_b32 v63, v71 offset:1524
	ds_read_b32 v64, v71 offset:1784
	ds_read_b32 v65, v71 offset:2044
	s_waitcnt lgkmcnt(15)
	v_mul_f32_e32 v2, v2, v74
	v_mul_f32_e32 v3, v3, v75
	v_mul_f32_e32 v4, v4, v76
	v_mul_f32_e32 v5, v5, v77
	v_mul_f32_e32 v6, v6, v78
	v_mul_f32_e32 v7, v7, v79
	v_mul_f32_e32 v8, v8, v80
	v_mul_f32_e32 v9, v9, v81
	v_cvt_pk_bf16_f32 v192, v2, v3
	v_cvt_pk_bf16_f32 v193, v4, v5
	v_cvt_pk_bf16_f32 v194, v6, v7
	v_cvt_pk_bf16_f32 v195, v8, v9
	global_store_dwordx4 v72, v[192:195], s[100:101] nt
	s_waitcnt lgkmcnt(15)
	v_mul_f32_e32 v10, v10, v74
	v_mul_f32_e32 v11, v11, v75
	v_mul_f32_e32 v12, v12, v76
	v_mul_f32_e32 v13, v13, v77
	v_mul_f32_e32 v14, v14, v78
	v_mul_f32_e32 v15, v15, v79
	v_mul_f32_e32 v16, v16, v80
	v_mul_f32_e32 v17, v17, v81
	v_cvt_pk_bf16_f32 v196, v10, v11
	v_cvt_pk_bf16_f32 v197, v12, v13
	v_cvt_pk_bf16_f32 v198, v14, v15
	v_cvt_pk_bf16_f32 v199, v16, v17
	v_add_u32_e32 v68, 0x8000, v72
	global_store_dwordx4 v68, v[196:199], s[100:101] nt
	s_waitcnt lgkmcnt(15)
	v_mul_f32_e32 v18, v18, v74
	v_mul_f32_e32 v19, v19, v75
	v_mul_f32_e32 v20, v20, v76
	v_mul_f32_e32 v21, v21, v77
	v_mul_f32_e32 v22, v22, v78
	v_mul_f32_e32 v23, v23, v79
	v_mul_f32_e32 v24, v24, v80
	v_mul_f32_e32 v25, v25, v81
	v_cvt_pk_bf16_f32 v200, v18, v19
	v_cvt_pk_bf16_f32 v201, v20, v21
	v_cvt_pk_bf16_f32 v202, v22, v23
	v_cvt_pk_bf16_f32 v203, v24, v25
	v_add_u32_e32 v67, 0x10000, v72
	global_store_dwordx4 v67, v[200:203], s[100:101] nt
	s_waitcnt lgkmcnt(15)
	v_mul_f32_e32 v26, v26, v74
	v_mul_f32_e32 v27, v27, v75
	v_mul_f32_e32 v28, v28, v76
	v_mul_f32_e32 v29, v29, v77
	v_mul_f32_e32 v30, v30, v78
	v_mul_f32_e32 v31, v31, v79
	v_mul_f32_e32 v32, v32, v80
	v_mul_f32_e32 v33, v33, v81
	v_cvt_pk_bf16_f32 v204, v26, v27
	v_cvt_pk_bf16_f32 v205, v28, v29
	v_cvt_pk_bf16_f32 v206, v30, v31
	v_cvt_pk_bf16_f32 v207, v32, v33
	v_add_u32_e32 v68, 0x18000, v72
	global_store_dwordx4 v68, v[204:207], s[100:101] nt
	s_waitcnt lgkmcnt(15)
	v_mul_f32_e32 v34, v34, v74
	v_mul_f32_e32 v35, v35, v75
	v_mul_f32_e32 v36, v36, v76
	v_mul_f32_e32 v37, v37, v77
	v_mul_f32_e32 v38, v38, v78
	v_mul_f32_e32 v39, v39, v79
	v_mul_f32_e32 v40, v40, v80
	v_mul_f32_e32 v41, v41, v81
	v_cvt_pk_bf16_f32 v208, v34, v35
	v_cvt_pk_bf16_f32 v209, v36, v37
	v_cvt_pk_bf16_f32 v210, v38, v39
	v_cvt_pk_bf16_f32 v211, v40, v41
	v_add_u32_e32 v67, 0x20000, v72
	global_store_dwordx4 v67, v[208:211], s[100:101] nt
	s_waitcnt lgkmcnt(15)
	v_mul_f32_e32 v42, v42, v74
	v_mul_f32_e32 v43, v43, v75
	v_mul_f32_e32 v44, v44, v76
	v_mul_f32_e32 v45, v45, v77
	v_mul_f32_e32 v46, v46, v78
	v_mul_f32_e32 v47, v47, v79
	v_mul_f32_e32 v48, v48, v80
	v_mul_f32_e32 v49, v49, v81
	v_cvt_pk_bf16_f32 v212, v42, v43
	v_cvt_pk_bf16_f32 v213, v44, v45
	v_cvt_pk_bf16_f32 v214, v46, v47
	v_cvt_pk_bf16_f32 v215, v48, v49
	v_add_u32_e32 v68, 0x28000, v72
	global_store_dwordx4 v68, v[212:215], s[100:101] nt
	s_waitcnt lgkmcnt(8)
	v_mul_f32_e32 v50, v50, v74
	v_mul_f32_e32 v51, v51, v75
	v_mul_f32_e32 v52, v52, v76
	v_mul_f32_e32 v53, v53, v77
	v_mul_f32_e32 v54, v54, v78
	v_mul_f32_e32 v55, v55, v79
	v_mul_f32_e32 v56, v56, v80
	v_mul_f32_e32 v57, v57, v81
	v_cvt_pk_bf16_f32 v216, v50, v51
	v_cvt_pk_bf16_f32 v217, v52, v53
	v_cvt_pk_bf16_f32 v218, v54, v55
	v_cvt_pk_bf16_f32 v219, v56, v57
	v_add_u32_e32 v67, 0x30000, v72
	global_store_dwordx4 v67, v[216:219], s[100:101] nt
	s_waitcnt lgkmcnt(0)
	v_mul_f32_e32 v58, v58, v74
	v_mul_f32_e32 v59, v59, v75
	v_mul_f32_e32 v60, v60, v76
	v_mul_f32_e32 v61, v61, v77
	v_mul_f32_e32 v62, v62, v78
	v_mul_f32_e32 v63, v63, v79
	v_mul_f32_e32 v64, v64, v80
	v_mul_f32_e32 v65, v65, v81
	v_cvt_pk_bf16_f32 v220, v58, v59
	v_cvt_pk_bf16_f32 v221, v60, v61
	v_cvt_pk_bf16_f32 v222, v62, v63
	v_cvt_pk_bf16_f32 v223, v64, v65
	v_add_u32_e32 v68, 0x38000, v72
	global_store_dwordx4 v68, v[220:223], s[100:101] nt

; #define LAS __attribute__((address_space(3)))
; #define TR_LOAD(p) __builtin_nontemporal_load(p)
; __device__ __forceinline__ TrItem tr_decode(int it, const float* const* in, unsigned char* ws, int lane) {
;     ...
;     const int rh = r >> 3, rl = r & 7, nq = ndb >> DL, kbh = rh / nq, dbh = rh - kbh * nq;
;     const int kb = (kbh << KL) + (rl >> DL), db = (dbh << DL) + (rl & ((1 << DL) - 1)), d0 = db * 64, k0 = kb * 64;
;     ...
;     const int kb = r / ndb, db = r - kb * ndb, d0 = db * 64, k0 = kb * 64;
;     ...
;     const int blk = d0 + 32 * ((lane & 15) >> 3);
;     const float* src = W; int s0 = blk;
;     if (kind == 1) { const int pn = blk >> 8, bj = (blk >> 7) & 1, o = blk & 127; src = bj ? W2 : W; s0 = pn * 128 + o; }
;     else if (kind == 2) s0 = win_src(blk);
;     TrItem t; t.src = src + (size_t)(k0 + (lane >> 4)) * N + s0 + 4 * (lane & 7); t.gain = gain ? gain + k0 + 8 * (lane & 7) : nullptr;
;     t.dst = WT + (size_t)(d0 + (lane >> 3)) * K + k0 + 8 * (lane & 7); t.N = N; t.K = K; t.nts = nts && TR_NTS;
; __device__ __forceinline__ void tr_all(const float* const* in, unsigned char* ws, LAS float* scr, int gw, int ngw, int lane, const TrRanges rg) {
;     ...
;     for (int i = 0; i < 16; ++i) v[i] = TR_LOAD((const f32x4*)(cur.src + (size_t)(4 * i) * cur.N));
;     for (int it = gw; it < TR_CNT; it += ngw) {
;         const int nit = it + ngw; const bool hn = nit < TR_CNT;
;         TrItem nx = cur; f32x4 w[16];
;         if (hn) { nx = tr_decode(rg.item(nit), in, ws, lane);
; #pragma unroll
;             for (int i = 0; i < 16; ++i) w[i] = TR_LOAD((const f32x4*)(nx.src + (size_t)(4 * i) * nx.N)); }
;         LAS float* wp = scr + (lane >> 4) * 65 + 4 * (lane & 15);
; #pragma unroll
;         for (int i = 0; i < 16; ++i) { wp[(4 * i) * 65 + 0] = v[i][0]; wp[(4 * i) * 65 + 1] = v[i][1]; wp[(4 * i) * 65 + 2] = v[i][2]; wp[(4 * i) * 65 + 3] = v[i][3]; }
.Lseam_cv_7:
	s_cmp_lt_u32 s98, 2
	s_cbranch_scc1 .LBB0_1403
	s_cmp_gt_u32 s98, 3
	s_cbranch_scc1 .LBB0_1403
	s_mov_b64 exec, -1
	s_lshl_b32 s99, s87, 1
	s_add_i32 s99, s99, s98
	s_add_i32 s99, s99, 0xffe
	s_lshr_b32 s100, s99, 3
	s_mul_i32 s101, s100, 0x5d2
	s_lshr_b32 s101, s101, 16
	s_mul_i32 vcc_lo, s101, 44
	s_sub_i32 s100, s100, vcc_lo
	s_and_b32 vcc_lo, s99, 7
	s_lshr_b32 vcc_hi, vcc_lo, 2
	s_lshl_b32 s101, s101, 1
	s_add_i32 s101, s101, vcc_hi
	s_and_b32 vcc_lo, vcc_lo, 3
	s_lshl_b32 s100, s100, 2
	s_add_i32 s100, s100, vcc_lo
	s_lshl_b32 s101, s101, 6
	s_lshl_b32 s100, s100, 6
	v_and_b32_e32 v66, 63, v1
	v_lshrrev_b32_e32 v67, 4, v66
	v_and_b32_e32 v68, 15, v66
	v_and_b32_e32 v73, 7, v66
	v_lshrrev_b32_e32 v72, 3, v66
	s_mul_i32 s99, s98, 0x4100
	v_mul_u32_u24_e32 v70, 0x104, v67
	v_lshl_add_u32 v70, v68, 4, v70
	v_add_u32_e32 v70, s99, v70
	v_mul_u32_u24_e32 v71, 0x820, v73
	v_lshl_add_u32 v71, v72, 2, v71
	v_add_u32_e32 v71, s99, v71
	s_mul_i32 s99, s101, 0x1600
	s_lshr_b32 vcc_lo, s100, 8
	s_lshl_b32 vcc_lo, vcc_lo, 7
	s_add_i32 s99, s99, vcc_lo
	s_and_b32 vcc_lo, s100, 0x7f
	s_add_i32 s99, s99, vcc_lo
	s_lshl_b32 s99, s99, 2
	v_mul_u32_u24_e32 v69, 0x5800, v67
	v_lshl_add_u32 v69, v68, 4, v69
	v_add_u32_e32 v69, s99, v69
	s_lshl_b32 s99, s100, 12
	s_lshl_b32 vcc_lo, s101, 1
	s_add_i32 s99, s99, vcc_lo
	v_lshlrev_b32_e32 v72, 12, v72
	v_lshl_add_u32 v72, v73, 4, v72
	v_add_u32_e32 v72, s99, v72
	s_lshl_b32 s99, s101, 2
	v_lshlrev_b32_e32 v73, 5, v73
	v_add_u32_e32 v73, s99, v73
	s_nop 0
	s_bitcmp1_b32 s100, 7
	v_readlane_b32 s100, v254, 6
	v_readlane_b32 s101, v254, 7
	v_readlane_b32 s98, v254, 8
	v_readlane_b32 s99, v254, 9
	s_nop 3
	s_cselect_b32 s100, s98, s100
	s_cselect_b32 s101, s99, s101
	v_readlane_b32 s98, v254, 4
	v_readlane_b32 s99, v254, 5
	global_load_dwordx4 v[2:5], v69, s[100:101] nt
	v_add_u32_e32 v68, 0x16000, v69
	global_load_dwordx4 v[6:9], v68, s[100:101] nt
	v_add_u32_e32 v67, 0x2c000, v69
	global_load_dwordx4 v[10:13], v67, s[100:101] nt
	v_add_u32_e32 v68, 0x42000, v69
	global_load_dwordx4 v[14:17], v68, s[100:101] nt
	v_add_u32_e32 v67, 0x58000, v69
	global_load_dwordx4 v[18:21], v67, s[100:101] nt
	v_add_u32_e32 v68, 0x6e000, v69
	global_load_dwordx4 v[22:25], v68, s[100:101] nt
	v_add_u32_e32 v67, 0x84000, v69
	global_load_dwordx4 v[26:29], v67, s[100:101] nt
	v_add_u32_e32 v68, 0x9a000, v69
	global_load_dwordx4 v[30:33], v68, s[100:101] nt
	v_add_u32_e32 v67, 0xb0000, v69
	global_load_dwordx4 v[34:37], v67, s[100:101] nt
	v_add_u32_e32 v68, 0xc6000, v69
	global_load_dwordx4 v[38:41], v68, s[100:101] nt
	v_add_u32_e32 v67, 0xdc000, v69
	global_load_dwordx4 v[42:45], v67, s[100:101] nt
	v_add_u32_e32 v68, 0xf2000, v69
	global_load_dwordx4 v[46:49], v68, s[100:101] nt
	v_add_u32_e32 v67, 0x108000, v69
	global_load_dwordx4 v[50:53], v67, s[100:101] nt
	v_add_u32_e32 v68, 0x11e000, v69
	global_load_dwordx4 v[54:57], v68, s[100:101] nt
	v_add_u32_e32 v67, 0x134000, v69
	global_load_dwordx4 v[58:61], v67, s[100:101] nt
	v_add_u32_e32 v68, 0x14a000, v69
	global_load_dwordx4 v[62:65], v68, s[100:101] nt
	global_load_dwordx4 v[74:77], v73, s[98:99]
	global_load_dwordx4 v[78:81], v73, s[98:99] offset:16
	s_waitcnt vmcnt(17)
	ds_write_b32 v70, v2
	ds_write_b32 v70, v3 offset:4
	ds_write_b32 v70, v4 offset:8
	ds_write_b32 v70, v5 offset:12
	s_waitcnt vmcnt(16)
	ds_write_b32 v70, v6 offset:1040
	ds_write_b32 v70, v7 offset:1044
	ds_write_b32 v70, v8 offset:1048
	ds_write_b32 v70, v9 offset:1052
	s_waitcnt vmcnt(15)
	ds_write_b32 v70, v10 offset:2080
	ds_write_b32 v70, v11 offset:2084
	ds_write_b32 v70, v12 offset:2088
	ds_write_b32 v70, v13 offset:2092
	s_waitcnt vmcnt(14)
	ds_write_b32 v70, v14 offset:3120
	ds_write_b32 v70, v15 offset:3124
	ds_write_b32 v70, v16 offset:3128
	ds_write_b32 v70, v17 offset:3132
	s_waitcnt vmcnt(13)
	ds_write_b32 v70, v18 offset:4160
	ds_write_b32 v70, v19 offset:4164
	ds_write_b32 v70, v20 offset:4168
	ds_write_b32 v70, v21 offset:4172
	s_waitcnt vmcnt(12)
	ds_write_b32 v70, v22 offset:5200
	ds_write_b32 v70, v23 offset:5204
	ds_write_b32 v70, v24 offset:5208
	ds_write_b32 v70, v25 offset:5212
	s_waitcnt vmcnt(11)
	ds_write_b32 v70, v26 offset:6240
	ds_write_b32 v70, v27 offset:6244
	ds_write_b32 v70, v28 offset:6248
	ds_write_b32 v70, v29 offset:6252
	s_waitcnt vmcnt(10)
	ds_write_b32 v70, v30 offset:7280
	ds_write_b32 v70, v31 offset:7284
	ds_write_b32 v70, v32 offset:7288
	ds_write_b32 v70, v33 offset:7292
	s_waitcnt vmcnt(9)
	ds_write_b32 v70, v34 offset:8320
	ds_write_b32 v70, v35 offset:8324
	ds_write_b32 v70, v36 offset:8328
	ds_write_b32 v70, v37 offset:8332
	s_waitcnt vmcnt(8)
	ds_write_b32 v70, v38 offset:9360
	ds_write_b32 v70, v39 offset:9364
	ds_write_b32 v70, v40 offset:9368
	ds_write_b32 v70, v41 offset:9372
	s_waitcnt vmcnt(7)
	ds_write_b32 v70, v42 offset:10400
	ds_write_b32 v70, v43 offset:10404
	ds_write_b32 v70, v44 offset:10408
	ds_write_b32 v70, v45 offset:10412
	s_waitcnt vmcnt(6)
	ds_write_b32 v70, v46 offset:11440
	ds_write_b32 v70, v47 offset:11444
	ds_write_b32 v70, v48 offset:11448
	ds_write_b32 v70, v49 offset:11452
	s_waitcnt vmcnt(5)
	ds_write_b32 v70, v50 offset:12480
	ds_write_b32 v70, v51 offset:12484
	ds_write_b32 v70, v52 offset:12488
	ds_write_b32 v70, v53 offset:12492
	s_waitcnt vmcnt(4)
	ds_write_b32 v70, v54 offset:13520
	ds_write_b32 v70, v55 offset:13524
	ds_write_b32 v70, v56 offset:13528
	ds_write_b32 v70, v57 offset:13532
	s_waitcnt vmcnt(3)
	ds_write_b32 v70, v58 offset:14560
	ds_write_b32 v70, v59 offset:14564
	ds_write_b32 v70, v60 offset:14568
	ds_write_b32 v70, v61 offset:14572
	s_waitcnt vmcnt(2)
; #define LAS __attribute__((address_space(3)))
; __device__ __forceinline__ unsigned cvtpk(float lo, float hi) { f32x2_t v = {lo, hi}; bf16x2_t b = __builtin_convertvector(v, bf16x2_t); return __builtin_bit_cast(unsigned, b); }
; __device__ __forceinline__ void tr_all(const float* const* in, unsigned char* ws, LAS float* scr, int gw, int ngw, int lane, const TrRanges rg) {
;     ...
;         for (int i = 0; i < 16; ++i) { wp[(4 * i) * 65 + 0] = v[i][0]; wp[(4 * i) * 65 + 1] = v[i][1]; wp[(4 * i) * 65 + 2] = v[i][2]; wp[(4 * i) * 65 + 3] = v[i][3]; }
;         f32x4 g0 = {1.f, 1.f, 1.f, 1.f}, g1 = {1.f, 1.f, 1.f, 1.f};
;         if (cur.gain) { g0 = *(const f32x4*)cur.gain; g1 = *(const f32x4*)(cur.gain + 4); }
;         asm volatile("s_waitcnt lgkmcnt(0)" ::: "memory");
;         const LAS float* rp = scr + (8 * (lane & 7)) * 65 + (lane >> 3);
; #pragma unroll
;         for (int j = 0; j < 8; ++j) { const LAS float* s = rp + 8 * j;
;             u32x4 o; o.x = cvtpk(s[0 * 65] * g0[0], s[1 * 65] * g0[1]); o.y = cvtpk(s[2 * 65] * g0[2], s[3 * 65] * g0[3]);
;             o.z = cvtpk(s[4 * 65] * g1[0], s[5 * 65] * g1[1]); o.w = cvtpk(s[6 * 65] * g1[2], s[7 * 65] * g1[3]);
;             if (cur.nts) __builtin_nontemporal_store(o, (u32x4*)(cur.dst + (size_t)(8 * j) * cur.K)); else *(u32x4*)(cur.dst + (size_t)(8 * j) * cur.K) = o; }
	ds_write_b32 v70, v62 offset:15600
	ds_write_b32 v70, v63 offset:15604
	ds_write_b32 v70, v64 offset:15608
	ds_write_b32 v70, v65 offset:15612
	s_add_u32 s100, s84, 0x8f00000
	s_addc_u32 s101, s85, 0
	s_waitcnt vmcnt(0) lgkmcnt(0)
	ds_read_b32 v2, v71
	ds_read_b32 v3, v71 offset:260
	ds_read_b32 v4, v71 offset:520
	ds_read_b32 v5, v71 offset:780
	ds_read_b32 v6, v71 offset:1040
	ds_read_b32 v7, v71 offset:1300
	ds_read_b32 v8, v71 offset:1560
	ds_read_b32 v9, v71 offset:1820
	ds_read_b32 v10, v71 offset:32
	ds_read_b32 v11, v71 offset:292
	ds_read_b32 v12, v71 offset:552
	ds_read_b32 v13, v71 offset:812
	ds_read_b32 v14, v71 offset:1072
	ds_read_b32 v15, v71 offset:1332
	ds_read_b32 v16, v71 offset:1592
	ds_read_b32 v17, v71 offset:1852
	ds_read_b32 v18, v71 offset:64
	ds_read_b32 v19, v71 offset:324
	ds_read_b32 v20, v71 offset:584
	ds_read_b32 v21, v71 offset:844
	ds_read_b32 v22, v71 offset:1104
	ds_read_b32 v23, v71 offset:1364
	ds_read_b32 v24, v71 offset:1624
	ds_read_b32 v25, v71 offset:1884
	ds_read_b32 v26, v71 offset:96
	ds_read_b32 v27, v71 offset:356
	ds_read_b32 v28, v71 offset:616
	ds_read_b32 v29, v71 offset:876
	ds_read_b32 v30, v71 offset:1136
	ds_read_b32 v31, v71 offset:1396
	ds_read_b32 v32, v71 offset:1656
	ds_read_b32 v33, v71 offset:1916
	ds_read_b32 v34, v71 offset:128
	ds_read_b32 v35, v71 offset:388
	ds_read_b32 v36, v71 offset:648
	ds_read_b32 v37, v71 offset:908
	ds_read_b32 v38, v71 offset:1168
	ds_read_b32 v39, v71 offset:1428
	ds_read_b32 v40, v71 offset:1688
	ds_read_b32 v41, v71 offset:1948
	ds_read_b32 v42, v71 offset:160
	ds_read_b32 v43, v71 offset:420
	ds_read_b32 v44, v71 offset:680
	ds_read_b32 v45, v71 offset:940
	ds_read_b32 v46, v71 offset:1200
	ds_read_b32 v47, v71 offset:1460
	ds_read_b32 v48, v71 offset:1720
	ds_read_b32 v49, v71 offset:1980
	ds_read_b32 v50, v71 offset:192
	ds_read_b32 v51, v71 offset:452
	ds_read_b32 v52, v71 offset:712
	ds_read_b32 v53, v71 offset:972
	ds_read_b32 v54, v71 offset:1232
	ds_read_b32 v55, v71 offset:1492
	ds_read_b32 v56, v71 offset:1752
	ds_read_b32 v57, v71 offset:2012
	ds_read_b32 v58, v71 offset:224
	ds_read_b32 v59, v71 offset:484
	ds_read_b32 v60, v71 offset:744
	ds_read_b32 v61, v71 offset:1004
	ds_read_b32 v62, v71 offset:1264
	ds_read_b32 v63, v71 offset:1524
	ds_read_b32 v64, v71 offset:1784
	ds_read_b32 v65, v71 offset:2044
	s_waitcnt lgkmcnt(15)
	v_mul_f32_e32 v2, v2, v74
	v_mul_f32_e32 v3, v3, v75
	v_mul_f32_e32 v4, v4, v76
	v_mul_f32_e32 v5, v5, v77
	v_mul_f32_e32 v6, v6, v78
	v_mul_f32_e32 v7, v7, v79
	v_mul_f32_e32 v8, v8, v80
	v_mul_f32_e32 v9, v9, v81
	v_cvt_pk_bf16_f32 v192, v2, v3
	v_cvt_pk_bf16_f32 v193, v4, v5
	v_cvt_pk_bf16_f32 v194, v6, v7
	v_cvt_pk_bf16_f32 v195, v8, v9
	global_store_dwordx4 v72, v[192:195], s[100:101] nt
	s_waitcnt lgkmcnt(15)
	v_mul_f32_e32 v10, v10, v74
	v_mul_f32_e32 v11, v11, v75
	v_mul_f32_e32 v12, v12, v76
	v_mul_f32_e32 v13, v13, v77
	v_mul_f32_e32 v14, v14, v78
	v_mul_f32_e32 v15, v15, v79
	v_mul_f32_e32 v16, v16, v80
	v_mul_f32_e32 v17, v17, v81
	v_cvt_pk_bf16_f32 v196, v10, v11
	v_cvt_pk_bf16_f32 v197, v12, v13
	v_cvt_pk_bf16_f32 v198, v14, v15
	v_cvt_pk_bf16_f32 v199, v16, v17
	v_add_u32_e32 v68, 0x8000, v72
	global_store_dwordx4 v68, v[196:199], s[100:101] nt
	s_waitcnt lgkmcnt(15)
	v_mul_f32_e32 v18, v18, v74
	v_mul_f32_e32 v19, v19, v75
	v_mul_f32_e32 v20, v20, v76
	v_mul_f32_e32 v21, v21, v77
	v_mul_f32_e32 v22, v22, v78
	v_mul_f32_e32 v23, v23, v79
	v_mul_f32_e32 v24, v24, v80
	v_mul_f32_e32 v25, v25, v81
	v_cvt_pk_bf16_f32 v200, v18, v19
	v_cvt_pk_bf16_f32 v201, v20, v21
	v_cvt_pk_bf16_f32 v202, v22, v23
	v_cvt_pk_bf16_f32 v203, v24, v25
	v_add_u32_e32 v67, 0x10000, v72
	global_store_dwordx4 v67, v[200:203], s[100:101] nt
	s_waitcnt lgkmcnt(15)
	v_mul_f32_e32 v26, v26, v74
	v_mul_f32_e32 v27, v27, v75
	v_mul_f32_e32 v28, v28, v76
	v_mul_f32_e32 v29, v29, v77
	v_mul_f32_e32 v30, v30, v78
	v_mul_f32_e32 v31, v31, v79
	v_mul_f32_e32 v32, v32, v80
	v_mul_f32_e32 v33, v33, v81
	v_cvt_pk_bf16_f32 v204, v26, v27
	v_cvt_pk_bf16_f32 v205, v28, v29
	v_cvt_pk_bf16_f32 v206, v30, v31
	v_cvt_pk_bf16_f32 v207, v32, v33
	v_add_u32_e32 v68, 0x18000, v72
	global_store_dwordx4 v68, v[204:207], s[100:101] nt
	s_waitcnt lgkmcnt(15)
	v_mul_f32_e32 v34, v34, v74
	v_mul_f32_e32 v35, v35, v75
	v_mul_f32_e32 v36, v36, v76
	v_mul_f32_e32 v37, v37, v77
	v_mul_f32_e32 v38, v38, v78
	v_mul_f32_e32 v39, v39, v79
	v_mul_f32_e32 v40, v40, v80
	v_mul_f32_e32 v41, v41, v81
	v_cvt_pk_bf16_f32 v208, v34, v35
	v_cvt_pk_bf16_f32 v209, v36, v37
	v_cvt_pk_bf16_f32 v210, v38, v39
	v_cvt_pk_bf16_f32 v211, v40, v41
	v_add_u32_e32 v67, 0x20000, v72
	global_store_dwordx4 v67, v[208:211], s[100:101] nt
	s_waitcnt lgkmcnt(15)
	v_mul_f32_e32 v42, v42, v74
	v_mul_f32_e32 v43, v43, v75
	v_mul_f32_e32 v44, v44, v76
	v_mul_f32_e32 v45, v45, v77
	v_mul_f32_e32 v46, v46, v78
	v_mul_f32_e32 v47, v47, v79
	v_mul_f32_e32 v48, v48, v80
	v_mul_f32_e32 v49, v49, v81
	v_cvt_pk_bf16_f32 v212, v42, v43
	v_cvt_pk_bf16_f32 v213, v44, v45
	v_cvt_pk_bf16_f32 v214, v46, v47
	v_cvt_pk_bf16_f32 v215, v48, v49
	v_add_u32_e32 v68, 0x28000, v72
	global_store_dwordx4 v68, v[212:215], s[100:101] nt
	s_waitcnt lgkmcnt(8)
	v_mul_f32_e32 v50, v50, v74
	v_mul_f32_e32 v51, v51, v75
	v_mul_f32_e32 v52, v52, v76
	v_mul_f32_e32 v53, v53, v77
	v_mul_f32_e32 v54, v54, v78
	v_mul_f32_e32 v55, v55, v79
	v_mul_f32_e32 v56, v56, v80
	v_mul_f32_e32 v57, v57, v81
	v_cvt_pk_bf16_f32 v216, v50, v51
	v_cvt_pk_bf16_f32 v217, v52, v53
	v_cvt_pk_bf16_f32 v218, v54, v55
	v_cvt_pk_bf16_f32 v219, v56, v57
	v_add_u32_e32 v67, 0x30000, v72
	global_store_dwordx4 v67, v[216:219], s[100:101] nt
	s_waitcnt lgkmcnt(0)
	v_mul_f32_e32 v58, v58, v74
	v_mul_f32_e32 v59, v59, v75
	v_mul_f32_e32 v60, v60, v76
	v_mul_f32_e32 v61, v61, v77
	v_mul_f32_e32 v62, v62, v78
	v_mul_f32_e32 v63, v63, v79
	v_mul_f32_e32 v64, v64, v80
	v_mul_f32_e32 v65, v65, v81
	v_cvt_pk_bf16_f32 v220, v58, v59
	v_cvt_pk_bf16_f32 v221, v60, v61
	v_cvt_pk_bf16_f32 v222, v62, v63
	v_cvt_pk_bf16_f32 v223, v64, v65
	v_add_u32_e32 v68, 0x38000, v72
	global_store_dwordx4 v68, v[220:223], s[100:101] nt

; #define LAS __attribute__((address_space(3)))
; #define TR_LOAD(p) __builtin_nontemporal_load(p)
; __device__ __forceinline__ TrItem tr_decode(int it, const float* const* in, unsigned char* ws, int lane) {
;     ...
;     const int rh = r >> 3, rl = r & 7, nq = ndb >> DL, kbh = rh / nq, dbh = rh - kbh * nq;
;     const int kb = (kbh << KL) + (rl >> DL), db = (dbh << DL) + (rl & ((1 << DL) - 1)), d0 = db * 64, k0 = kb * 64;
;     ...
;     const int kb = r / ndb, db = r - kb * ndb, d0 = db * 64, k0 = kb * 64;
;     ...
;     const int blk = d0 + 32 * ((lane & 15) >> 3);
;     const float* src = W; int s0 = blk;
;     if (kind == 1) { const int pn = blk >> 8, bj = (blk >> 7) & 1, o = blk & 127; src = bj ? W2 : W; s0 = pn * 128 + o; }
;     else if (kind == 2) s0 = win_src(blk);
;     TrItem t; t.src = src + (size_t)(k0 + (lane >> 4)) * N + s0 + 4 * (lane & 7); t.gain = gain ? gain + k0 + 8 * (lane & 7) : nullptr;
;     t.dst = WT + (size_t)(d0 + (lane >> 3)) * K + k0 + 8 * (lane & 7); t.N = N; t.K = K; t.nts = nts && TR_NTS;
; __device__ __forceinline__ void tr_all(const float* const* in, unsigned char* ws, LAS float* scr, int gw, int ngw, int lane, const TrRanges rg) {
;     ...
;     for (int i = 0; i < 16; ++i) v[i] = TR_LOAD((const f32x4*)(cur.src + (size_t)(4 * i) * cur.N));
;     for (int it = gw; it < TR_CNT; it += ngw) {
;         const int nit = it + ngw; const bool hn = nit < TR_CNT;
;         TrItem nx = cur; f32x4 w[16];
;         if (hn) { nx = tr_decode(rg.item(nit), in, ws, lane);
; #pragma unroll
;             for (int i = 0; i < 16; ++i) w[i] = TR_LOAD((const f32x4*)(nx.src + (size_t)(4 * i) * nx.N)); }
;         LAS float* wp = scr + (lane >> 4) * 65 + 4 * (lane & 15);
; #pragma unroll
;         for (int i = 0; i < 16; ++i) { wp[(4 * i) * 65 + 0] = v[i][0]; wp[(4 * i) * 65 + 1] = v[i][1]; wp[(4 * i) * 65 + 2] = v[i][2]; wp[(4 * i) * 65 + 3] = v[i][3]; }
.Lseam_cv_8:
	s_cmp_lt_u32 s98, 2
	s_cbranch_scc1 .LBB0_1494
	s_cmp_gt_u32 s98, 3
	s_cbranch_scc1 .LBB0_1494
	s_mov_b64 exec, -1
	s_lshl_b32 s99, s87, 1
	s_add_i32 s99, s99, s98
	s_add_i32 s99, s99, 0x11fe
	s_lshr_b32 s100, s99, 3
	s_mul_i32 s101, s100, 0x5d2
	s_lshr_b32 s101, s101, 16
	s_mul_i32 vcc_lo, s101, 44
	s_sub_i32 s100, s100, vcc_lo
	s_and_b32 vcc_lo, s99, 7
	s_lshr_b32 vcc_hi, vcc_lo, 2
	s_lshl_b32 s101, s101, 1
	s_add_i32 s101, s101, vcc_hi
	s_and_b32 vcc_lo, vcc_lo, 3
	s_lshl_b32 s100, s100, 2
	s_add_i32 s100, s100, vcc_lo
	s_lshl_b32 s101, s101, 6
	s_lshl_b32 s100, s100, 6
	v_and_b32_e32 v66, 63, v1
	v_lshrrev_b32_e32 v67, 4, v66
	v_and_b32_e32 v68, 15, v66
	v_and_b32_e32 v73, 7, v66
	v_lshrrev_b32_e32 v72, 3, v66
	s_mul_i32 s99, s98, 0x4100
	v_mul_u32_u24_e32 v70, 0x104, v67
	v_lshl_add_u32 v70, v68, 4, v70
	v_add_u32_e32 v70, s99, v70
	v_mul_u32_u24_e32 v71, 0x820, v73
	v_lshl_add_u32 v71, v72, 2, v71
	v_add_u32_e32 v71, s99, v71
	s_mul_i32 s99, s101, 0x1600
	s_lshr_b32 vcc_lo, s100, 8
	s_lshl_b32 vcc_lo, vcc_lo, 7
	s_add_i32 s99, s99, vcc_lo
	s_and_b32 vcc_lo, s100, 0x7f
	s_add_i32 s99, s99, vcc_lo
	s_lshl_b32 s99, s99, 2
	v_mul_u32_u24_e32 v69, 0x5800, v67
	v_lshl_add_u32 v69, v68, 4, v69
	v_add_u32_e32 v69, s99, v69
	s_lshl_b32 s99, s100, 12
	s_lshl_b32 vcc_lo, s101, 1
	s_add_i32 s99, s99, vcc_lo
	v_lshlrev_b32_e32 v72, 12, v72
	v_lshl_add_u32 v72, v73, 4, v72
	v_add_u32_e32 v72, s99, v72
	s_lshl_b32 s99, s101, 2
	v_lshlrev_b32_e32 v73, 5, v73
	v_add_u32_e32 v73, s99, v73
	s_nop 0
	s_bitcmp1_b32 s100, 7
	v_readlane_b32 s100, v254, 6
	v_readlane_b32 s101, v254, 7
	v_readlane_b32 s98, v254, 8
	v_readlane_b32 s99, v254, 9
	s_nop 3
	s_cselect_b32 s100, s98, s100
	s_cselect_b32 s101, s99, s101
	v_readlane_b32 s98, v254, 4
	v_readlane_b32 s99, v254, 5
	global_load_dwordx4 v[2:5], v69, s[100:101] nt
	v_add_u32_e32 v68, 0x16000, v69
	global_load_dwordx4 v[6:9], v68, s[100:101] nt
	v_add_u32_e32 v67, 0x2c000, v69
	global_load_dwordx4 v[10:13], v67, s[100:101] nt
	v_add_u32_e32 v68, 0x42000, v69
	global_load_dwordx4 v[14:17], v68, s[100:101] nt
	v_add_u32_e32 v67, 0x58000, v69
	global_load_dwordx4 v[18:21], v67, s[100:101] nt
	v_add_u32_e32 v68, 0x6e000, v69
	global_load_dwordx4 v[22:25], v68, s[100:101] nt
	v_add_u32_e32 v67, 0x84000, v69
	global_load_dwordx4 v[26:29], v67, s[100:101] nt
	v_add_u32_e32 v68, 0x9a000, v69
	global_load_dwordx4 v[30:33], v68, s[100:101] nt
	v_add_u32_e32 v67, 0xb0000, v69
	global_load_dwordx4 v[34:37], v67, s[100:101] nt
	v_add_u32_e32 v68, 0xc6000, v69
	global_load_dwordx4 v[38:41], v68, s[100:101] nt
	v_add_u32_e32 v67, 0xdc000, v69
	global_load_dwordx4 v[42:45], v67, s[100:101] nt
	v_add_u32_e32 v68, 0xf2000, v69
	global_load_dwordx4 v[46:49], v68, s[100:101] nt
	v_add_u32_e32 v67, 0x108000, v69
	global_load_dwordx4 v[50:53], v67, s[100:101] nt
	v_add_u32_e32 v68, 0x11e000, v69
	global_load_dwordx4 v[54:57], v68, s[100:101] nt
	v_add_u32_e32 v67, 0x134000, v69
	global_load_dwordx4 v[58:61], v67, s[100:101] nt
	v_add_u32_e32 v68, 0x14a000, v69
	global_load_dwordx4 v[62:65], v68, s[100:101] nt
	global_load_dwordx4 v[74:77], v73, s[98:99]
	global_load_dwordx4 v[78:81], v73, s[98:99] offset:16
	s_waitcnt vmcnt(17)
	ds_write_b32 v70, v2
	ds_write_b32 v70, v3 offset:4
	ds_write_b32 v70, v4 offset:8
	ds_write_b32 v70, v5 offset:12
	s_waitcnt vmcnt(16)
	ds_write_b32 v70, v6 offset:1040
	ds_write_b32 v70, v7 offset:1044
	ds_write_b32 v70, v8 offset:1048
	ds_write_b32 v70, v9 offset:1052
	s_waitcnt vmcnt(15)
	ds_write_b32 v70, v10 offset:2080
	ds_write_b32 v70, v11 offset:2084
	ds_write_b32 v70, v12 offset:2088
	ds_write_b32 v70, v13 offset:2092
	s_waitcnt vmcnt(14)
	ds_write_b32 v70, v14 offset:3120
	ds_write_b32 v70, v15 offset:3124
	ds_write_b32 v70, v16 offset:3128
	ds_write_b32 v70, v17 offset:3132
	s_waitcnt vmcnt(13)
	ds_write_b32 v70, v18 offset:4160
	ds_write_b32 v70, v19 offset:4164
	ds_write_b32 v70, v20 offset:4168
	ds_write_b32 v70, v21 offset:4172
	s_waitcnt vmcnt(12)
	ds_write_b32 v70, v22 offset:5200
	ds_write_b32 v70, v23 offset:5204
	ds_write_b32 v70, v24 offset:5208
	ds_write_b32 v70, v25 offset:5212
	s_waitcnt vmcnt(11)
	ds_write_b32 v70, v26 offset:6240
	ds_write_b32 v70, v27 offset:6244
	ds_write_b32 v70, v28 offset:6248
	ds_write_b32 v70, v29 offset:6252
	s_waitcnt vmcnt(10)
	ds_write_b32 v70, v30 offset:7280
	ds_write_b32 v70, v31 offset:7284
	ds_write_b32 v70, v32 offset:7288
	ds_write_b32 v70, v33 offset:7292
	s_waitcnt vmcnt(9)
	ds_write_b32 v70, v34 offset:8320
	ds_write_b32 v70, v35 offset:8324
	ds_write_b32 v70, v36 offset:8328
	ds_write_b32 v70, v37 offset:8332
	s_waitcnt vmcnt(8)
	ds_write_b32 v70, v38 offset:9360
	ds_write_b32 v70, v39 offset:9364
	ds_write_b32 v70, v40 offset:9368
	ds_write_b32 v70, v41 offset:9372
	s_waitcnt vmcnt(7)
	ds_write_b32 v70, v42 offset:10400
	ds_write_b32 v70, v43 offset:10404
	ds_write_b32 v70, v44 offset:10408
	ds_write_b32 v70, v45 offset:10412
	s_waitcnt vmcnt(6)
	ds_write_b32 v70, v46 offset:11440
	ds_write_b32 v70, v47 offset:11444
	ds_write_b32 v70, v48 offset:11448
	ds_write_b32 v70, v49 offset:11452
	s_waitcnt vmcnt(5)
	ds_write_b32 v70, v50 offset:12480
	ds_write_b32 v70, v51 offset:12484
	ds_write_b32 v70, v52 offset:12488
	ds_write_b32 v70, v53 offset:12492
	s_waitcnt vmcnt(4)
	ds_write_b32 v70, v54 offset:13520
	ds_write_b32 v70, v55 offset:13524
	ds_write_b32 v70, v56 offset:13528
	ds_write_b32 v70, v57 offset:13532
	s_waitcnt vmcnt(3)
	ds_write_b32 v70, v58 offset:14560
	ds_write_b32 v70, v59 offset:14564
	ds_write_b32 v70, v60 offset:14568
	ds_write_b32 v70, v61 offset:14572
	s_waitcnt vmcnt(2)
; #define LAS __attribute__((address_space(3)))
; __device__ __forceinline__ unsigned cvtpk(float lo, float hi) { f32x2_t v = {lo, hi}; bf16x2_t b = __builtin_convertvector(v, bf16x2_t); return __builtin_bit_cast(unsigned, b); }
; __device__ __forceinline__ void tr_all(const float* const* in, unsigned char* ws, LAS float* scr, int gw, int ngw, int lane, const TrRanges rg) {
;     ...
;         for (int i = 0; i < 16; ++i) { wp[(4 * i) * 65 + 0] = v[i][0]; wp[(4 * i) * 65 + 1] = v[i][1]; wp[(4 * i) * 65 + 2] = v[i][2]; wp[(4 * i) * 65 + 3] = v[i][3]; }
;         f32x4 g0 = {1.f, 1.f, 1.f, 1.f}, g1 = {1.f, 1.f, 1.f, 1.f};
;         if (cur.gain) { g0 = *(const f32x4*)cur.gain; g1 = *(const f32x4*)(cur.gain + 4); }
;         asm volatile("s_waitcnt lgkmcnt(0)" ::: "memory");
;         const LAS float* rp = scr + (8 * (lane & 7)) * 65 + (lane >> 3);
; #pragma unroll
;         for (int j = 0; j < 8; ++j) { const LAS float* s = rp + 8 * j;
;             u32x4 o; o.x = cvtpk(s[0 * 65] * g0[0], s[1 * 65] * g0[1]); o.y = cvtpk(s[2 * 65] * g0[2], s[3 * 65] * g0[3]);
;             o.z = cvtpk(s[4 * 65] * g1[0], s[5 * 65] * g1[1]); o.w = cvtpk(s[6 * 65] * g1[2], s[7 * 65] * g1[3]);
;             if (cur.nts) __builtin_nontemporal_store(o, (u32x4*)(cur.dst + (size_t)(8 * j) * cur.K)); else *(u32x4*)(cur.dst + (size_t)(8 * j) * cur.K) = o; }
	ds_write_b32 v70, v62 offset:15600
	ds_write_b32 v70, v63 offset:15604
	ds_write_b32 v70, v64 offset:15608
	ds_write_b32 v70, v65 offset:15612
	s_add_u32 s100, s84, 0x8f00000
	s_addc_u32 s101, s85, 0
	s_waitcnt vmcnt(0) lgkmcnt(0)
	ds_read_b32 v2, v71
	ds_read_b32 v3, v71 offset:260
	ds_read_b32 v4, v71 offset:520
	ds_read_b32 v5, v71 offset:780
	ds_read_b32 v6, v71 offset:1040
	ds_read_b32 v7, v71 offset:1300
	ds_read_b32 v8, v71 offset:1560
	ds_read_b32 v9, v71 offset:1820
	ds_read_b32 v10, v71 offset:32
	ds_read_b32 v11, v71 offset:292
	ds_read_b32 v12, v71 offset:552
	ds_read_b32 v13, v71 offset:812
	ds_read_b32 v14, v71 offset:1072
	ds_read_b32 v15, v71 offset:1332
	ds_read_b32 v16, v71 offset:1592
	ds_read_b32 v17, v71 offset:1852
	ds_read_b32 v18, v71 offset:64
	ds_read_b32 v19, v71 offset:324
	ds_read_b32 v20, v71 offset:584
	ds_read_b32 v21, v71 offset:844
	ds_read_b32 v22, v71 offset:1104
	ds_read_b32 v23, v71 offset:1364
	ds_read_b32 v24, v71 offset:1624
	ds_read_b32 v25, v71 offset:1884
	ds_read_b32 v26, v71 offset:96
	ds_read_b32 v27, v71 offset:356
	ds_read_b32 v28, v71 offset:616
	ds_read_b32 v29, v71 offset:876
	ds_read_b32 v30, v71 offset:1136
	ds_read_b32 v31, v71 offset:1396
	ds_read_b32 v32, v71 offset:1656
	ds_read_b32 v33, v71 offset:1916
	ds_read_b32 v34, v71 offset:128
	ds_read_b32 v35, v71 offset:388
	ds_read_b32 v36, v71 offset:648
	ds_read_b32 v37, v71 offset:908
	ds_read_b32 v38, v71 offset:1168
	ds_read_b32 v39, v71 offset:1428
	ds_read_b32 v40, v71 offset:1688
	ds_read_b32 v41, v71 offset:1948
	ds_read_b32 v42, v71 offset:160
	ds_read_b32 v43, v71 offset:420
	ds_read_b32 v44, v71 offset:680
	ds_read_b32 v45, v71 offset:940
	ds_read_b32 v46, v71 offset:1200
	ds_read_b32 v47, v71 offset:1460
	ds_read_b32 v48, v71 offset:1720
	ds_read_b32 v49, v71 offset:1980
	ds_read_b32 v50, v71 offset:192
	ds_read_b32 v51, v71 offset:452
	ds_read_b32 v52, v71 offset:712
	ds_read_b32 v53, v71 offset:972
	ds_read_b32 v54, v71 offset:1232
	ds_read_b32 v55, v71 offset:1492
	ds_read_b32 v56, v71 offset:1752
	ds_read_b32 v57, v71 offset:2012
	ds_read_b32 v58, v71 offset:224
	ds_read_b32 v59, v71 offset:484
	ds_read_b32 v60, v71 offset:744
	ds_read_b32 v61, v71 offset:1004
	ds_read_b32 v62, v71 offset:1264
	ds_read_b32 v63, v71 offset:1524
	ds_read_b32 v64, v71 offset:1784
	ds_read_b32 v65, v71 offset:2044
	s_waitcnt lgkmcnt(15)
	v_mul_f32_e32 v2, v2, v74
	v_mul_f32_e32 v3, v3, v75
	v_mul_f32_e32 v4, v4, v76
	v_mul_f32_e32 v5, v5, v77
	v_mul_f32_e32 v6, v6, v78
	v_mul_f32_e32 v7, v7, v79
	v_mul_f32_e32 v8, v8, v80
	v_mul_f32_e32 v9, v9, v81
	v_cvt_pk_bf16_f32 v192, v2, v3
	v_cvt_pk_bf16_f32 v193, v4, v5
	v_cvt_pk_bf16_f32 v194, v6, v7
	v_cvt_pk_bf16_f32 v195, v8, v9
	global_store_dwordx4 v72, v[192:195], s[100:101] nt
	s_waitcnt lgkmcnt(15)
	v_mul_f32_e32 v10, v10, v74
	v_mul_f32_e32 v11, v11, v75
	v_mul_f32_e32 v12, v12, v76
	v_mul_f32_e32 v13, v13, v77
	v_mul_f32_e32 v14, v14, v78
	v_mul_f32_e32 v15, v15, v79
	v_mul_f32_e32 v16, v16, v80
	v_mul_f32_e32 v17, v17, v81
	v_cvt_pk_bf16_f32 v196, v10, v11
	v_cvt_pk_bf16_f32 v197, v12, v13
	v_cvt_pk_bf16_f32 v198, v14, v15
	v_cvt_pk_bf16_f32 v199, v16, v17
	v_add_u32_e32 v68, 0x8000, v72
	global_store_dwordx4 v68, v[196:199], s[100:101] nt
	s_waitcnt lgkmcnt(15)
	v_mul_f32_e32 v18, v18, v74
	v_mul_f32_e32 v19, v19, v75
	v_mul_f32_e32 v20, v20, v76
	v_mul_f32_e32 v21, v21, v77
	v_mul_f32_e32 v22, v22, v78
	v_mul_f32_e32 v23, v23, v79
	v_mul_f32_e32 v24, v24, v80
	v_mul_f32_e32 v25, v25, v81
	v_cvt_pk_bf16_f32 v200, v18, v19
	v_cvt_pk_bf16_f32 v201, v20, v21
	v_cvt_pk_bf16_f32 v202, v22, v23
	v_cvt_pk_bf16_f32 v203, v24, v25
	v_add_u32_e32 v67, 0x10000, v72
	global_store_dwordx4 v67, v[200:203], s[100:101] nt
	s_waitcnt lgkmcnt(15)
	v_mul_f32_e32 v26, v26, v74
	v_mul_f32_e32 v27, v27, v75
	v_mul_f32_e32 v28, v28, v76
	v_mul_f32_e32 v29, v29, v77
	v_mul_f32_e32 v30, v30, v78
	v_mul_f32_e32 v31, v31, v79
	v_mul_f32_e32 v32, v32, v80
	v_mul_f32_e32 v33, v33, v81
	v_cvt_pk_bf16_f32 v204, v26, v27
	v_cvt_pk_bf16_f32 v205, v28, v29
	v_cvt_pk_bf16_f32 v206, v30, v31
	v_cvt_pk_bf16_f32 v207, v32, v33
	v_add_u32_e32 v68, 0x18000, v72
	global_store_dwordx4 v68, v[204:207], s[100:101] nt
	s_waitcnt lgkmcnt(15)
	v_mul_f32_e32 v34, v34, v74
	v_mul_f32_e32 v35, v35, v75
	v_mul_f32_e32 v36, v36, v76
	v_mul_f32_e32 v37, v37, v77
	v_mul_f32_e32 v38, v38, v78
	v_mul_f32_e32 v39, v39, v79
	v_mul_f32_e32 v40, v40, v80
	v_mul_f32_e32 v41, v41, v81
	v_cvt_pk_bf16_f32 v208, v34, v35
	v_cvt_pk_bf16_f32 v209, v36, v37
	v_cvt_pk_bf16_f32 v210, v38, v39
	v_cvt_pk_bf16_f32 v211, v40, v41
	v_add_u32_e32 v67, 0x20000, v72
	global_store_dwordx4 v67, v[208:211], s[100:101] nt
	s_waitcnt lgkmcnt(15)
	v_mul_f32_e32 v42, v42, v74
	v_mul_f32_e32 v43, v43, v75
	v_mul_f32_e32 v44, v44, v76
	v_mul_f32_e32 v45, v45, v77
	v_mul_f32_e32 v46, v46, v78
	v_mul_f32_e32 v47, v47, v79
	v_mul_f32_e32 v48, v48, v80
	v_mul_f32_e32 v49, v49, v81
	v_cvt_pk_bf16_f32 v212, v42, v43
	v_cvt_pk_bf16_f32 v213, v44, v45
	v_cvt_pk_bf16_f32 v214, v46, v47
	v_cvt_pk_bf16_f32 v215, v48, v49
	v_add_u32_e32 v68, 0x28000, v72
	global_store_dwordx4 v68, v[212:215], s[100:101] nt
	s_waitcnt lgkmcnt(8)
	v_mul_f32_e32 v50, v50, v74
	v_mul_f32_e32 v51, v51, v75
	v_mul_f32_e32 v52, v52, v76
	v_mul_f32_e32 v53, v53, v77
	v_mul_f32_e32 v54, v54, v78
	v_mul_f32_e32 v55, v55, v79
	v_mul_f32_e32 v56, v56, v80
	v_mul_f32_e32 v57, v57, v81
	v_cvt_pk_bf16_f32 v216, v50, v51
	v_cvt_pk_bf16_f32 v217, v52, v53
	v_cvt_pk_bf16_f32 v218, v54, v55
	v_cvt_pk_bf16_f32 v219, v56, v57
	v_add_u32_e32 v67, 0x30000, v72
	global_store_dwordx4 v67, v[216:219], s[100:101] nt
	s_waitcnt lgkmcnt(0)
	v_mul_f32_e32 v58, v58, v74
	v_mul_f32_e32 v59, v59, v75
	v_mul_f32_e32 v60, v60, v76
	v_mul_f32_e32 v61, v61, v77
	v_mul_f32_e32 v62, v62, v78
	v_mul_f32_e32 v63, v63, v79
	v_mul_f32_e32 v64, v64, v80
	v_mul_f32_e32 v65, v65, v81
	v_cvt_pk_bf16_f32 v220, v58, v59
	v_cvt_pk_bf16_f32 v221, v60, v61
	v_cvt_pk_bf16_f32 v222, v62, v63
	v_cvt_pk_bf16_f32 v223, v64, v65
	v_add_u32_e32 v68, 0x38000, v72
	global_store_dwordx4 v68, v[220:223], s[100:101] nt

; #define LAS __attribute__((address_space(3)))
; #define TR_LOAD(p) __builtin_nontemporal_load(p)
; __device__ __forceinline__ TrItem tr_decode(int it, const float* const* in, unsigned char* ws, int lane) {
;     ...
;     const int rh = r >> 3, rl = r & 7, nq = ndb >> DL, kbh = rh / nq, dbh = rh - kbh * nq;
;     const int kb = (kbh << KL) + (rl >> DL), db = (dbh << DL) + (rl & ((1 << DL) - 1)), d0 = db * 64, k0 = kb * 64;
;     ...
;     const int kb = r / ndb, db = r - kb * ndb, d0 = db * 64, k0 = kb * 64;
;     ...
;     const int blk = d0 + 32 * ((lane & 15) >> 3);
;     const float* src = W; int s0 = blk;
;     if (kind == 1) { const int pn = blk >> 8, bj = (blk >> 7) & 1, o = blk & 127; src = bj ? W2 : W; s0 = pn * 128 + o; }
;     else if (kind == 2) s0 = win_src(blk);
;     TrItem t; t.src = src + (size_t)(k0 + (lane >> 4)) * N + s0 + 4 * (lane & 7); t.gain = gain ? gain + k0 + 8 * (lane & 7) : nullptr;
;     t.dst = WT + (size_t)(d0 + (lane >> 3)) * K + k0 + 8 * (lane & 7); t.N = N; t.K = K; t.nts = nts && TR_NTS;
; __device__ __forceinline__ void tr_all(const float* const* in, unsigned char* ws, LAS float* scr, int gw, int ngw, int lane, const TrRanges rg) {
;     ...
;     for (int i = 0; i < 16; ++i) v[i] = TR_LOAD((const f32x4*)(cur.src + (size_t)(4 * i) * cur.N));
;     for (int it = gw; it < TR_CNT; it += ngw) {
;         const int nit = it + ngw; const bool hn = nit < TR_CNT;
;         TrItem nx = cur; f32x4 w[16];
;         if (hn) { nx = tr_decode(rg.item(nit), in, ws, lane);
; #pragma unroll
;             for (int i = 0; i < 16; ++i) w[i] = TR_LOAD((const f32x4*)(nx.src + (size_t)(4 * i) * nx.N)); }
;         LAS float* wp = scr + (lane >> 4) * 65 + 4 * (lane & 15);
; #pragma unroll
;         for (int i = 0; i < 16; ++i) { wp[(4 * i) * 65 + 0] = v[i][0]; wp[(4 * i) * 65 + 1] = v[i][1]; wp[(4 * i) * 65 + 2] = v[i][2]; wp[(4 * i) * 65 + 3] = v[i][3]; }
.Lseam_cv_9:
	s_cmp_lt_u32 s98, 2
	s_cbranch_scc1 .LBB0_1570
	s_cmp_gt_u32 s98, 3
	s_cbranch_scc1 .LBB0_1570
	s_mov_b64 exec, -1
	s_lshl_b32 s99, s87, 1
	s_add_i32 s99, s99, s98
	s_add_i32 s99, s99, 0x13fe
	s_lshr_b32 s100, s99, 3
	s_mul_i32 s101, s100, 0x5d2
	s_lshr_b32 s101, s101, 16
	s_mul_i32 vcc_lo, s101, 44
	s_sub_i32 s100, s100, vcc_lo
	s_and_b32 vcc_lo, s99, 7
	s_lshr_b32 vcc_hi, vcc_lo, 2
	s_lshl_b32 s101, s101, 1
	s_add_i32 s101, s101, vcc_hi
	s_and_b32 vcc_lo, vcc_lo, 3
	s_lshl_b32 s100, s100, 2
	s_add_i32 s100, s100, vcc_lo
	s_lshl_b32 s101, s101, 6
	s_lshl_b32 s100, s100, 6
	v_and_b32_e32 v66, 63, v1
	v_lshrrev_b32_e32 v67, 4, v66
	v_and_b32_e32 v68, 15, v66
	v_and_b32_e32 v73, 7, v66
	v_lshrrev_b32_e32 v72, 3, v66
	s_mul_i32 s99, s98, 0x4100
	v_mul_u32_u24_e32 v70, 0x104, v67
	v_lshl_add_u32 v70, v68, 4, v70
	v_add_u32_e32 v70, s99, v70
	v_mul_u32_u24_e32 v71, 0x820, v73
	v_lshl_add_u32 v71, v72, 2, v71
	v_add_u32_e32 v71, s99, v71
	s_mul_i32 s99, s101, 0x1600
	s_lshr_b32 vcc_lo, s100, 8
	s_lshl_b32 vcc_lo, vcc_lo, 7
	s_add_i32 s99, s99, vcc_lo
	s_and_b32 vcc_lo, s100, 0x7f
	s_add_i32 s99, s99, vcc_lo
	s_lshl_b32 s99, s99, 2
	v_mul_u32_u24_e32 v69, 0x5800, v67
	v_lshl_add_u32 v69, v68, 4, v69
	v_add_u32_e32 v69, s99, v69
	s_lshl_b32 s99, s100, 12
	s_lshl_b32 vcc_lo, s101, 1
	s_add_i32 s99, s99, vcc_lo
	v_lshlrev_b32_e32 v72, 12, v72
	v_lshl_add_u32 v72, v73, 4, v72
	v_add_u32_e32 v72, s99, v72
	s_lshl_b32 s99, s101, 2
	v_lshlrev_b32_e32 v73, 5, v73
	v_add_u32_e32 v73, s99, v73
	s_nop 0
	s_bitcmp1_b32 s100, 7
	v_readlane_b32 s100, v254, 6
	v_readlane_b32 s101, v254, 7
	v_readlane_b32 s98, v254, 8
	v_readlane_b32 s99, v254, 9
	s_nop 3
	s_cselect_b32 s100, s98, s100
	s_cselect_b32 s101, s99, s101
	v_readlane_b32 s98, v254, 4
	v_readlane_b32 s99, v254, 5
	global_load_dwordx4 v[2:5], v69, s[100:101] nt
	v_add_u32_e32 v68, 0x16000, v69
	global_load_dwordx4 v[6:9], v68, s[100:101] nt
	v_add_u32_e32 v67, 0x2c000, v69
	global_load_dwordx4 v[10:13], v67, s[100:101] nt
	v_add_u32_e32 v68, 0x42000, v69
	global_load_dwordx4 v[14:17], v68, s[100:101] nt
	v_add_u32_e32 v67, 0x58000, v69
	global_load_dwordx4 v[18:21], v67, s[100:101] nt
	v_add_u32_e32 v68, 0x6e000, v69
	global_load_dwordx4 v[22:25], v68, s[100:101] nt
	v_add_u32_e32 v67, 0x84000, v69
	global_load_dwordx4 v[26:29], v67, s[100:101] nt
	v_add_u32_e32 v68, 0x9a000, v69
	global_load_dwordx4 v[30:33], v68, s[100:101] nt
	v_add_u32_e32 v67, 0xb0000, v69
	global_load_dwordx4 v[34:37], v67, s[100:101] nt
	v_add_u32_e32 v68, 0xc6000, v69
	global_load_dwordx4 v[38:41], v68, s[100:101] nt
	v_add_u32_e32 v67, 0xdc000, v69
	global_load_dwordx4 v[42:45], v67, s[100:101] nt
	v_add_u32_e32 v68, 0xf2000, v69
	global_load_dwordx4 v[46:49], v68, s[100:101] nt
	v_add_u32_e32 v67, 0x108000, v69
	global_load_dwordx4 v[50:53], v67, s[100:101] nt
	v_add_u32_e32 v68, 0x11e000, v69
	global_load_dwordx4 v[54:57], v68, s[100:101] nt
	v_add_u32_e32 v67, 0x134000, v69
	global_load_dwordx4 v[58:61], v67, s[100:101] nt
	v_add_u32_e32 v68, 0x14a000, v69
	global_load_dwordx4 v[62:65], v68, s[100:101] nt
	global_load_dwordx4 v[74:77], v73, s[98:99]
	global_load_dwordx4 v[78:81], v73, s[98:99] offset:16
	s_waitcnt vmcnt(17)
	ds_write_b32 v70, v2
	ds_write_b32 v70, v3 offset:4
	ds_write_b32 v70, v4 offset:8
	ds_write_b32 v70, v5 offset:12
	s_waitcnt vmcnt(16)
	ds_write_b32 v70, v6 offset:1040
	ds_write_b32 v70, v7 offset:1044
	ds_write_b32 v70, v8 offset:1048
	ds_write_b32 v70, v9 offset:1052
	s_waitcnt vmcnt(15)
	ds_write_b32 v70, v10 offset:2080
	ds_write_b32 v70, v11 offset:2084
	ds_write_b32 v70, v12 offset:2088
	ds_write_b32 v70, v13 offset:2092
	s_waitcnt vmcnt(14)
	ds_write_b32 v70, v14 offset:3120
	ds_write_b32 v70, v15 offset:3124
	ds_write_b32 v70, v16 offset:3128
	ds_write_b32 v70, v17 offset:3132
	s_waitcnt vmcnt(13)
	ds_write_b32 v70, v18 offset:4160
	ds_write_b32 v70, v19 offset:4164
	ds_write_b32 v70, v20 offset:4168
	ds_write_b32 v70, v21 offset:4172
	s_waitcnt vmcnt(12)
	ds_write_b32 v70, v22 offset:5200
	ds_write_b32 v70, v23 offset:5204
	ds_write_b32 v70, v24 offset:5208
	ds_write_b32 v70, v25 offset:5212
	s_waitcnt vmcnt(11)
	ds_write_b32 v70, v26 offset:6240
	ds_write_b32 v70, v27 offset:6244
	ds_write_b32 v70, v28 offset:6248
	ds_write_b32 v70, v29 offset:6252
	s_waitcnt vmcnt(10)
	ds_write_b32 v70, v30 offset:7280
	ds_write_b32 v70, v31 offset:7284
	ds_write_b32 v70, v32 offset:7288
	ds_write_b32 v70, v33 offset:7292
	s_waitcnt vmcnt(9)
	ds_write_b32 v70, v34 offset:8320
	ds_write_b32 v70, v35 offset:8324
	ds_write_b32 v70, v36 offset:8328
	ds_write_b32 v70, v37 offset:8332
	s_waitcnt vmcnt(8)
	ds_write_b32 v70, v38 offset:9360
	ds_write_b32 v70, v39 offset:9364
	ds_write_b32 v70, v40 offset:9368
	ds_write_b32 v70, v41 offset:9372
	s_waitcnt vmcnt(7)
	ds_write_b32 v70, v42 offset:10400
	ds_write_b32 v70, v43 offset:10404
	ds_write_b32 v70, v44 offset:10408
	ds_write_b32 v70, v45 offset:10412
	s_waitcnt vmcnt(6)
	ds_write_b32 v70, v46 offset:11440
	ds_write_b32 v70, v47 offset:11444
	ds_write_b32 v70, v48 offset:11448
	ds_write_b32 v70, v49 offset:11452
	s_waitcnt vmcnt(5)
	ds_write_b32 v70, v50 offset:12480
	ds_write_b32 v70, v51 offset:12484
	ds_write_b32 v70, v52 offset:12488
	ds_write_b32 v70, v53 offset:12492
	s_waitcnt vmcnt(4)
	ds_write_b32 v70, v54 offset:13520
	ds_write_b32 v70, v55 offset:13524
	ds_write_b32 v70, v56 offset:13528
	ds_write_b32 v70, v57 offset:13532
	s_waitcnt vmcnt(3)
	ds_write_b32 v70, v58 offset:14560
	ds_write_b32 v70, v59 offset:14564
	ds_write_b32 v70, v60 offset:14568
	ds_write_b32 v70, v61 offset:14572
	s_waitcnt vmcnt(2)
; #define LAS __attribute__((address_space(3)))
; __device__ __forceinline__ unsigned cvtpk(float lo, float hi) { f32x2_t v = {lo, hi}; bf16x2_t b = __builtin_convertvector(v, bf16x2_t); return __builtin_bit_cast(unsigned, b); }
; __device__ __forceinline__ void tr_all(const float* const* in, unsigned char* ws, LAS float* scr, int gw, int ngw, int lane, const TrRanges rg) {
;     ...
;         for (int i = 0; i < 16; ++i) { wp[(4 * i) * 65 + 0] = v[i][0]; wp[(4 * i) * 65 + 1] = v[i][1]; wp[(4 * i) * 65 + 2] = v[i][2]; wp[(4 * i) * 65 + 3] = v[i][3]; }
;         f32x4 g0 = {1.f, 1.f, 1.f, 1.f}, g1 = {1.f, 1.f, 1.f, 1.f};
;         if (cur.gain) { g0 = *(const f32x4*)cur.gain; g1 = *(const f32x4*)(cur.gain + 4); }
;         asm volatile("s_waitcnt lgkmcnt(0)" ::: "memory");
;         const LAS float* rp = scr + (8 * (lane & 7)) * 65 + (lane >> 3);
; #pragma unroll
;         for (int j = 0; j < 8; ++j) { const LAS float* s = rp + 8 * j;
;             u32x4 o; o.x = cvtpk(s[0 * 65] * g0[0], s[1 * 65] * g0[1]); o.y = cvtpk(s[2 * 65] * g0[2], s[3 * 65] * g0[3]);
;             o.z = cvtpk(s[4 * 65] * g1[0], s[5 * 65] * g1[1]); o.w = cvtpk(s[6 * 65] * g1[2], s[7 * 65] * g1[3]);
;             if (cur.nts) __builtin_nontemporal_store(o, (u32x4*)(cur.dst + (size_t)(8 * j) * cur.K)); else *(u32x4*)(cur.dst + (size_t)(8 * j) * cur.K) = o; }
	ds_write_b32 v70, v62 offset:15600
	ds_write_b32 v70, v63 offset:15604
	ds_write_b32 v70, v64 offset:15608
	ds_write_b32 v70, v65 offset:15612
	s_add_u32 s100, s84, 0x8f00000
	s_addc_u32 s101, s85, 0
	s_waitcnt vmcnt(0) lgkmcnt(0)
	ds_read_b32 v2, v71
	ds_read_b32 v3, v71 offset:260
	ds_read_b32 v4, v71 offset:520
	ds_read_b32 v5, v71 offset:780
	ds_read_b32 v6, v71 offset:1040
	ds_read_b32 v7, v71 offset:1300
	ds_read_b32 v8, v71 offset:1560
	ds_read_b32 v9, v71 offset:1820
	ds_read_b32 v10, v71 offset:32
	ds_read_b32 v11, v71 offset:292
	ds_read_b32 v12, v71 offset:552
	ds_read_b32 v13, v71 offset:812
	ds_read_b32 v14, v71 offset:1072
	ds_read_b32 v15, v71 offset:1332
	ds_read_b32 v16, v71 offset:1592
	ds_read_b32 v17, v71 offset:1852
	ds_read_b32 v18, v71 offset:64
	ds_read_b32 v19, v71 offset:324
	ds_read_b32 v20, v71 offset:584
	ds_read_b32 v21, v71 offset:844
	ds_read_b32 v22, v71 offset:1104
	ds_read_b32 v23, v71 offset:1364
	ds_read_b32 v24, v71 offset:1624
	ds_read_b32 v25, v71 offset:1884
	ds_read_b32 v26, v71 offset:96
	ds_read_b32 v27, v71 offset:356
	ds_read_b32 v28, v71 offset:616
	ds_read_b32 v29, v71 offset:876
	ds_read_b32 v30, v71 offset:1136
	ds_read_b32 v31, v71 offset:1396
	ds_read_b32 v32, v71 offset:1656
	ds_read_b32 v33, v71 offset:1916
	ds_read_b32 v34, v71 offset:128
	ds_read_b32 v35, v71 offset:388
	ds_read_b32 v36, v71 offset:648
	ds_read_b32 v37, v71 offset:908
	ds_read_b32 v38, v71 offset:1168
	ds_read_b32 v39, v71 offset:1428
	ds_read_b32 v40, v71 offset:1688
	ds_read_b32 v41, v71 offset:1948
	ds_read_b32 v42, v71 offset:160
	ds_read_b32 v43, v71 offset:420
	ds_read_b32 v44, v71 offset:680
	ds_read_b32 v45, v71 offset:940
	ds_read_b32 v46, v71 offset:1200
	ds_read_b32 v47, v71 offset:1460
	ds_read_b32 v48, v71 offset:1720
	ds_read_b32 v49, v71 offset:1980
	ds_read_b32 v50, v71 offset:192
	ds_read_b32 v51, v71 offset:452
	ds_read_b32 v52, v71 offset:712
	ds_read_b32 v53, v71 offset:972
	ds_read_b32 v54, v71 offset:1232
	ds_read_b32 v55, v71 offset:1492
	ds_read_b32 v56, v71 offset:1752
	ds_read_b32 v57, v71 offset:2012
	ds_read_b32 v58, v71 offset:224
	ds_read_b32 v59, v71 offset:484
	ds_read_b32 v60, v71 offset:744
	ds_read_b32 v61, v71 offset:1004
	ds_read_b32 v62, v71 offset:1264
	ds_read_b32 v63, v71 offset:1524
	ds_read_b32 v64, v71 offset:1784
	ds_read_b32 v65, v71 offset:2044
	s_waitcnt lgkmcnt(15)
	v_mul_f32_e32 v2, v2, v74
	v_mul_f32_e32 v3, v3, v75
	v_mul_f32_e32 v4, v4, v76
	v_mul_f32_e32 v5, v5, v77
	v_mul_f32_e32 v6, v6, v78
	v_mul_f32_e32 v7, v7, v79
	v_mul_f32_e32 v8, v8, v80
	v_mul_f32_e32 v9, v9, v81
	v_cvt_pk_bf16_f32 v192, v2, v3
	v_cvt_pk_bf16_f32 v193, v4, v5
	v_cvt_pk_bf16_f32 v194, v6, v7
	v_cvt_pk_bf16_f32 v195, v8, v9
	global_store_dwordx4 v72, v[192:195], s[100:101] nt
	s_waitcnt lgkmcnt(15)
	v_mul_f32_e32 v10, v10, v74
	v_mul_f32_e32 v11, v11, v75
	v_mul_f32_e32 v12, v12, v76
	v_mul_f32_e32 v13, v13, v77
	v_mul_f32_e32 v14, v14, v78
	v_mul_f32_e32 v15, v15, v79
	v_mul_f32_e32 v16, v16, v80
	v_mul_f32_e32 v17, v17, v81
	v_cvt_pk_bf16_f32 v196, v10, v11
	v_cvt_pk_bf16_f32 v197, v12, v13
	v_cvt_pk_bf16_f32 v198, v14, v15
	v_cvt_pk_bf16_f32 v199, v16, v17
	v_add_u32_e32 v68, 0x8000, v72
	global_store_dwordx4 v68, v[196:199], s[100:101] nt
	s_waitcnt lgkmcnt(15)
	v_mul_f32_e32 v18, v18, v74
	v_mul_f32_e32 v19, v19, v75
	v_mul_f32_e32 v20, v20, v76
	v_mul_f32_e32 v21, v21, v77
	v_mul_f32_e32 v22, v22, v78
	v_mul_f32_e32 v23, v23, v79
	v_mul_f32_e32 v24, v24, v80
	v_mul_f32_e32 v25, v25, v81
	v_cvt_pk_bf16_f32 v200, v18, v19
	v_cvt_pk_bf16_f32 v201, v20, v21
	v_cvt_pk_bf16_f32 v202, v22, v23
	v_cvt_pk_bf16_f32 v203, v24, v25
	v_add_u32_e32 v67, 0x10000, v72
	global_store_dwordx4 v67, v[200:203], s[100:101] nt
	s_waitcnt lgkmcnt(15)
	v_mul_f32_e32 v26, v26, v74
	v_mul_f32_e32 v27, v27, v75
	v_mul_f32_e32 v28, v28, v76
	v_mul_f32_e32 v29, v29, v77
	v_mul_f32_e32 v30, v30, v78
	v_mul_f32_e32 v31, v31, v79
	v_mul_f32_e32 v32, v32, v80
	v_mul_f32_e32 v33, v33, v81
	v_cvt_pk_bf16_f32 v204, v26, v27
	v_cvt_pk_bf16_f32 v205, v28, v29
	v_cvt_pk_bf16_f32 v206, v30, v31
	v_cvt_pk_bf16_f32 v207, v32, v33
	v_add_u32_e32 v68, 0x18000, v72
	global_store_dwordx4 v68, v[204:207], s[100:101] nt
	s_waitcnt lgkmcnt(15)
	v_mul_f32_e32 v34, v34, v74
	v_mul_f32_e32 v35, v35, v75
	v_mul_f32_e32 v36, v36, v76
	v_mul_f32_e32 v37, v37, v77
	v_mul_f32_e32 v38, v38, v78
	v_mul_f32_e32 v39, v39, v79
	v_mul_f32_e32 v40, v40, v80
	v_mul_f32_e32 v41, v41, v81
	v_cvt_pk_bf16_f32 v208, v34, v35
	v_cvt_pk_bf16_f32 v209, v36, v37
	v_cvt_pk_bf16_f32 v210, v38, v39
	v_cvt_pk_bf16_f32 v211, v40, v41
	v_add_u32_e32 v67, 0x20000, v72
	global_store_dwordx4 v67, v[208:211], s[100:101] nt
	s_waitcnt lgkmcnt(15)
	v_mul_f32_e32 v42, v42, v74
	v_mul_f32_e32 v43, v43, v75
	v_mul_f32_e32 v44, v44, v76
	v_mul_f32_e32 v45, v45, v77
	v_mul_f32_e32 v46, v46, v78
	v_mul_f32_e32 v47, v47, v79
	v_mul_f32_e32 v48, v48, v80
	v_mul_f32_e32 v49, v49, v81
	v_cvt_pk_bf16_f32 v212, v42, v43
	v_cvt_pk_bf16_f32 v213, v44, v45
	v_cvt_pk_bf16_f32 v214, v46, v47
	v_cvt_pk_bf16_f32 v215, v48, v49
	v_add_u32_e32 v68, 0x28000, v72
	global_store_dwordx4 v68, v[212:215], s[100:101] nt
	s_waitcnt lgkmcnt(8)
	v_mul_f32_e32 v50, v50, v74
	v_mul_f32_e32 v51, v51, v75
	v_mul_f32_e32 v52, v52, v76
	v_mul_f32_e32 v53, v53, v77
	v_mul_f32_e32 v54, v54, v78
	v_mul_f32_e32 v55, v55, v79
	v_mul_f32_e32 v56, v56, v80
	v_mul_f32_e32 v57, v57, v81
	v_cvt_pk_bf16_f32 v216, v50, v51
	v_cvt_pk_bf16_f32 v217, v52, v53
	v_cvt_pk_bf16_f32 v218, v54, v55
	v_cvt_pk_bf16_f32 v219, v56, v57
	v_add_u32_e32 v67, 0x30000, v72
	global_store_dwordx4 v67, v[216:219], s[100:101] nt
	s_waitcnt lgkmcnt(0)
	v_mul_f32_e32 v58, v58, v74
	v_mul_f32_e32 v59, v59, v75
	v_mul_f32_e32 v60, v60, v76
	v_mul_f32_e32 v61, v61, v77
	v_mul_f32_e32 v62, v62, v78
	v_mul_f32_e32 v63, v63, v79
	v_mul_f32_e32 v64, v64, v80
	v_mul_f32_e32 v65, v65, v81
	v_cvt_pk_bf16_f32 v220, v58, v59
	v_cvt_pk_bf16_f32 v221, v60, v61
	v_cvt_pk_bf16_f32 v222, v62, v63
	v_cvt_pk_bf16_f32 v223, v64, v65
	v_add_u32_e32 v68, 0x38000, v72
	global_store_dwordx4 v68, v[220:223], s[100:101] nt
